# K-loop load phases 2 and 4: issue the six LDS-DMA loads before the eight B-fragment ds_reads (all nine GEMM loops)
# speedup vs baseline: 1.0111x; 1.0054x over previous
.LBB0_511:
	s_add_i32 s62, s30, 2
	s_add_u32 s63, s28, 0x80
	s_addc_u32 s31, s29, 0
	s_add_i32 s66, 0, 0x10000
	s_cmp_eq_u32 s54, s30
	s_cselect_b32 s31, s7, s31
	s_cselect_b32 s30, s6, s63
	v_add_u32_e32 v156, s66, v141
	s_cselect_b32 s65, s27, s61
	s_cselect_b32 s64, s26, s60
	s_add_i32 s63, 0, 0x14000
	ds_read_b128 v[144:147], v156
	ds_read_b128 v[148:151], v156 offset:1024
	ds_read_b128 v[152:155], v156 offset:2048
	ds_read_b128 v[160:163], v156 offset:3072
	v_add_u32_e32 v156, s63, v141
	ds_read_b128 v[164:167], v156
	ds_read_b128 v[168:171], v156 offset:1024
	ds_read_b128 v[172:175], v156 offset:2048
	ds_read_b128 v[176:179], v156 offset:3072
	v_lshl_add_u64 v[156:157], s[28:29], 0, v[136:137]
	s_add_i32 m0, s47, 0xc000
	ds_read_b128 v[180:183], v143
	ds_read_b128 v[184:187], v143 offset:1024
	ds_read_b128 v[188:191], v143 offset:2048
	ds_read_b128 v[192:195], v143 offset:3072
	ds_read_b128 v[214:217], v143 offset:4096
	ds_read_b128 v[218:221], v143 offset:5120
	ds_read_b128 v[222:225], v143 offset:6144
	ds_read_b128 v[226:229], v143 offset:7168
	global_load_lds_dwordx4 v[156:157], off
	v_lshl_add_u64 v[156:157], s[28:29], 0, v[138:139]
	s_add_i32 m0, s47, 0xe000
	s_nop 0
	global_load_lds_dwordx4 v[156:157], off
	s_waitcnt vmcnt(8)
	s_waitcnt lgkmcnt(0)
	s_barrier
	s_setprio 1
	s_waitcnt lgkmcnt(0)
	v_mfma_f32_16x16x32_bf16 v[122:125], v[144:147], v[180:183], v[122:125]
	v_mfma_f32_16x16x32_bf16 v[118:121], v[152:155], v[180:183], v[118:121]
	v_mfma_f32_16x16x32_bf16 v[110:113], v[144:147], v[188:191], v[110:113]
	v_mfma_f32_16x16x32_bf16 v[102:105], v[152:155], v[188:191], v[102:105]
	v_mfma_f32_16x16x32_bf16 v[94:97], v[144:147], v[214:217], v[94:97]
	v_mfma_f32_16x16x32_bf16 v[84:87], v[152:155], v[214:217], v[84:87]
	v_mfma_f32_16x16x32_bf16 v[76:79], v[144:147], v[222:225], v[76:79]
	v_mfma_f32_16x16x32_bf16 v[68:71], v[152:155], v[222:225], v[68:71]
	v_mfma_f32_16x16x32_bf16 v[122:125], v[148:151], v[184:187], v[122:125]
	v_mfma_f32_16x16x32_bf16 v[118:121], v[160:163], v[184:187], v[118:121]
	v_mfma_f32_16x16x32_bf16 v[110:113], v[148:151], v[192:195], v[110:113]
	v_mfma_f32_16x16x32_bf16 v[102:105], v[160:163], v[192:195], v[102:105]
	v_mfma_f32_16x16x32_bf16 v[94:97], v[148:151], v[218:221], v[94:97]
	v_mfma_f32_16x16x32_bf16 v[84:87], v[160:163], v[218:221], v[84:87]
	v_mfma_f32_16x16x32_bf16 v[76:79], v[148:151], v[226:229], v[76:79]
	v_mfma_f32_16x16x32_bf16 v[68:71], v[160:163], v[226:229], v[68:71]
	s_setprio 0
	s_setprio 1
	v_mfma_f32_16x16x32_bf16 v[126:129], v[164:167], v[180:183], v[126:129]
	v_mfma_f32_16x16x32_bf16 v[114:117], v[172:175], v[180:183], v[114:117]
	v_mfma_f32_16x16x32_bf16 v[106:109], v[164:167], v[188:191], v[106:109]
	v_mfma_f32_16x16x32_bf16 v[98:101], v[172:175], v[188:191], v[98:101]
	v_mfma_f32_16x16x32_bf16 v[88:91], v[164:167], v[214:217], v[88:91]
	v_mfma_f32_16x16x32_bf16 v[80:83], v[172:175], v[214:217], v[80:83]
	v_mfma_f32_16x16x32_bf16 v[72:75], v[164:167], v[222:225], v[72:75]
	v_mfma_f32_16x16x32_bf16 v[64:67], v[172:175], v[222:225], v[64:67]
	v_mfma_f32_16x16x32_bf16 v[126:129], v[168:171], v[184:187], v[126:129]
	v_mfma_f32_16x16x32_bf16 v[114:117], v[176:179], v[184:187], v[114:117]
	v_mfma_f32_16x16x32_bf16 v[106:109], v[168:171], v[192:195], v[106:109]
	v_mfma_f32_16x16x32_bf16 v[98:101], v[176:179], v[192:195], v[98:101]
	v_mfma_f32_16x16x32_bf16 v[88:91], v[168:171], v[218:221], v[88:91]
	v_mfma_f32_16x16x32_bf16 v[80:83], v[176:179], v[218:221], v[80:83]
	v_mfma_f32_16x16x32_bf16 v[72:75], v[168:171], v[226:229], v[72:75]
	v_mfma_f32_16x16x32_bf16 v[64:67], v[176:179], v[226:229], v[64:67]
	s_setprio 0
	s_barrier
	s_add_i32 s66, s66, s44
	v_lshl_add_u64 v[156:157], s[64:65], 0, v[92:93]
	s_mov_b32 m0, s66
	global_load_lds_dwordx4 v[156:157], off
	s_add_i32 m0, s66, 0x2000
	v_lshl_add_u64 v[230:231], s[64:65], 0, v[134:135]
	s_add_u32 s64, s64, s10
	s_addc_u32 s65, s65, s11
	s_add_i32 s63, s63, s44
	global_load_lds_dwordx4 v[230:231], off
	v_lshl_add_u64 v[232:233], s[64:65], 0, v[92:93]
	s_mov_b32 m0, s63
	v_lshl_add_u64 v[234:235], s[64:65], 0, v[134:135]
	global_load_lds_dwordx4 v[232:233], off
	s_add_i32 m0, s63, 0x2000
	v_lshl_add_u64 v[236:237], s[30:31], 0, v[130:131]
	global_load_lds_dwordx4 v[234:235], off
	s_mov_b32 m0, s47
	v_lshl_add_u64 v[238:239], s[30:31], 0, v[132:133]
	global_load_lds_dwordx4 v[236:237], off
	s_mov_b32 m0, s48
	s_nop 0
	global_load_lds_dwordx4 v[238:239], off
	ds_read_b128 v[180:183], v143 offset:16384
	ds_read_b128 v[184:187], v143 offset:17408
	ds_read_b128 v[188:191], v143 offset:18432
	ds_read_b128 v[192:195], v143 offset:19456
	ds_read_b128 v[214:217], v143 offset:20480
	ds_read_b128 v[218:221], v143 offset:21504
	ds_read_b128 v[222:225], v143 offset:22528
	ds_read_b128 v[226:229], v143 offset:23552
	s_waitcnt vmcnt(8)
	s_waitcnt lgkmcnt(0)
	s_barrier
	s_setprio 1
	s_waitcnt lgkmcnt(0)
	v_mfma_f32_16x16x32_bf16 v[60:63], v[144:147], v[180:183], v[60:63]
	v_mfma_f32_16x16x32_bf16 v[52:55], v[152:155], v[180:183], v[52:55]
	v_mfma_f32_16x16x32_bf16 v[44:47], v[144:147], v[188:191], v[44:47]
	v_mfma_f32_16x16x32_bf16 v[36:39], v[152:155], v[188:191], v[36:39]
	v_mfma_f32_16x16x32_bf16 v[28:31], v[144:147], v[214:217], v[28:31]
	v_mfma_f32_16x16x32_bf16 v[20:23], v[152:155], v[214:217], v[20:23]
	v_mfma_f32_16x16x32_bf16 v[12:15], v[144:147], v[222:225], v[12:15]
	v_mfma_f32_16x16x32_bf16 v[4:7], v[152:155], v[222:225], v[4:7]
	v_mfma_f32_16x16x32_bf16 v[60:63], v[148:151], v[184:187], v[60:63]
	v_mfma_f32_16x16x32_bf16 v[52:55], v[160:163], v[184:187], v[52:55]
	v_mfma_f32_16x16x32_bf16 v[44:47], v[148:151], v[192:195], v[44:47]
	v_mfma_f32_16x16x32_bf16 v[36:39], v[160:163], v[192:195], v[36:39]
	v_mfma_f32_16x16x32_bf16 v[28:31], v[148:151], v[218:221], v[28:31]
	v_mfma_f32_16x16x32_bf16 v[20:23], v[160:163], v[218:221], v[20:23]
	v_mfma_f32_16x16x32_bf16 v[12:15], v[148:151], v[226:229], v[12:15]
	v_mfma_f32_16x16x32_bf16 v[4:7], v[160:163], v[226:229], v[4:7]
	s_setprio 0
	s_setprio 1
	v_mfma_f32_16x16x32_bf16 v[56:59], v[164:167], v[180:183], v[56:59]
	v_mfma_f32_16x16x32_bf16 v[48:51], v[172:175], v[180:183], v[48:51]
	v_mfma_f32_16x16x32_bf16 v[40:43], v[164:167], v[188:191], v[40:43]
	v_mfma_f32_16x16x32_bf16 v[32:35], v[172:175], v[188:191], v[32:35]
	v_mfma_f32_16x16x32_bf16 v[24:27], v[164:167], v[214:217], v[24:27]
	v_mfma_f32_16x16x32_bf16 v[16:19], v[172:175], v[214:217], v[16:19]
	v_mfma_f32_16x16x32_bf16 v[8:11], v[164:167], v[222:225], v[8:11]
	v_mfma_f32_16x16x32_bf16 v[0:3], v[172:175], v[222:225], v[0:3]
	v_mfma_f32_16x16x32_bf16 v[56:59], v[168:171], v[184:187], v[56:59]
	v_mfma_f32_16x16x32_bf16 v[48:51], v[176:179], v[184:187], v[48:51]
	v_mfma_f32_16x16x32_bf16 v[40:43], v[168:171], v[192:195], v[40:43]
	v_mfma_f32_16x16x32_bf16 v[32:35], v[176:179], v[192:195], v[32:35]
	v_mfma_f32_16x16x32_bf16 v[24:27], v[168:171], v[218:221], v[24:27]
	v_mfma_f32_16x16x32_bf16 v[16:19], v[176:179], v[218:221], v[16:19]
	v_mfma_f32_16x16x32_bf16 v[8:11], v[168:171], v[226:229], v[8:11]
	v_mfma_f32_16x16x32_bf16 v[0:3], v[176:179], v[226:229], v[0:3]
	s_setprio 0
	s_barrier
	s_add_i32 s63, 0, 0x18000
	v_add_u32_e32 v159, s63, v141
	s_add_i32 s64, 0, 0x1c000
	ds_read_b128 v[144:147], v159
	ds_read_b128 v[148:151], v159 offset:1024
	ds_read_b128 v[152:155], v159 offset:2048
	ds_read_b128 v[160:163], v159 offset:3072
	v_add_u32_e32 v159, s64, v141
	ds_read_b128 v[164:167], v159
	ds_read_b128 v[168:171], v159 offset:1024
	ds_read_b128 v[172:175], v159 offset:2048
	ds_read_b128 v[176:179], v159 offset:3072
	s_add_u32 s30, s30, s14
	s_addc_u32 s31, s31, s15
	s_mov_b32 m0, s49
	v_lshl_add_u64 v[240:241], s[30:31], 0, v[130:131]
	ds_read_b128 v[180:183], v143 offset:32768
	ds_read_b128 v[184:187], v143 offset:33792
	ds_read_b128 v[188:191], v143 offset:34816
	ds_read_b128 v[192:195], v143 offset:35840
	ds_read_b128 v[214:217], v143 offset:36864
	ds_read_b128 v[218:221], v143 offset:37888
	ds_read_b128 v[222:225], v143 offset:38912
	ds_read_b128 v[226:229], v143 offset:39936
	global_load_lds_dwordx4 v[240:241], off
	v_lshl_add_u64 v[240:241], s[30:31], 0, v[132:133]
	s_mov_b32 m0, s50
	s_nop 0
	global_load_lds_dwordx4 v[240:241], off
	s_waitcnt vmcnt(8)
	s_waitcnt lgkmcnt(0)
	s_barrier
	s_setprio 1
	s_waitcnt lgkmcnt(0)
	v_mfma_f32_16x16x32_bf16 v[122:125], v[144:147], v[180:183], v[122:125]
	v_mfma_f32_16x16x32_bf16 v[118:121], v[152:155], v[180:183], v[118:121]
	v_mfma_f32_16x16x32_bf16 v[110:113], v[144:147], v[188:191], v[110:113]
	v_mfma_f32_16x16x32_bf16 v[102:105], v[152:155], v[188:191], v[102:105]
	v_mfma_f32_16x16x32_bf16 v[94:97], v[144:147], v[214:217], v[94:97]
	v_mfma_f32_16x16x32_bf16 v[84:87], v[152:155], v[214:217], v[84:87]
	v_mfma_f32_16x16x32_bf16 v[76:79], v[144:147], v[222:225], v[76:79]
	v_mfma_f32_16x16x32_bf16 v[68:71], v[152:155], v[222:225], v[68:71]
	v_mfma_f32_16x16x32_bf16 v[122:125], v[148:151], v[184:187], v[122:125]
	v_mfma_f32_16x16x32_bf16 v[118:121], v[160:163], v[184:187], v[118:121]
	v_mfma_f32_16x16x32_bf16 v[110:113], v[148:151], v[192:195], v[110:113]
	v_mfma_f32_16x16x32_bf16 v[102:105], v[160:163], v[192:195], v[102:105]
	v_mfma_f32_16x16x32_bf16 v[94:97], v[148:151], v[218:221], v[94:97]
	v_mfma_f32_16x16x32_bf16 v[84:87], v[160:163], v[218:221], v[84:87]
	v_mfma_f32_16x16x32_bf16 v[76:79], v[148:151], v[226:229], v[76:79]
	v_mfma_f32_16x16x32_bf16 v[68:71], v[160:163], v[226:229], v[68:71]
	s_setprio 0
	s_setprio 1
	v_mfma_f32_16x16x32_bf16 v[126:129], v[164:167], v[180:183], v[126:129]
	v_mfma_f32_16x16x32_bf16 v[114:117], v[172:175], v[180:183], v[114:117]
	v_mfma_f32_16x16x32_bf16 v[106:109], v[164:167], v[188:191], v[106:109]
	v_mfma_f32_16x16x32_bf16 v[98:101], v[172:175], v[188:191], v[98:101]
	v_mfma_f32_16x16x32_bf16 v[88:91], v[164:167], v[214:217], v[88:91]
	v_mfma_f32_16x16x32_bf16 v[80:83], v[172:175], v[214:217], v[80:83]
	v_mfma_f32_16x16x32_bf16 v[72:75], v[164:167], v[222:225], v[72:75]
	v_mfma_f32_16x16x32_bf16 v[64:67], v[172:175], v[222:225], v[64:67]
	v_mfma_f32_16x16x32_bf16 v[126:129], v[168:171], v[184:187], v[126:129]
	v_mfma_f32_16x16x32_bf16 v[114:117], v[176:179], v[184:187], v[114:117]
	v_mfma_f32_16x16x32_bf16 v[106:109], v[168:171], v[192:195], v[106:109]
	v_mfma_f32_16x16x32_bf16 v[98:101], v[176:179], v[192:195], v[98:101]
	v_mfma_f32_16x16x32_bf16 v[88:91], v[168:171], v[218:221], v[88:91]
	v_mfma_f32_16x16x32_bf16 v[80:83], v[176:179], v[218:221], v[80:83]
	v_mfma_f32_16x16x32_bf16 v[72:75], v[168:171], v[226:229], v[72:75]
	v_mfma_f32_16x16x32_bf16 v[64:67], v[176:179], v[226:229], v[64:67]
	s_setprio 0
	s_barrier
	s_add_i32 s30, s63, s44
	v_lshl_add_u64 v[156:157], v[156:157], 0, s[80:81]
	s_mov_b32 m0, s30
	global_load_lds_dwordx4 v[156:157], off
	v_lshl_add_u64 v[156:157], v[230:231], 0, s[80:81]
	s_add_i32 m0, s30, 0x2000
	s_add_i32 s30, s64, s44
	global_load_lds_dwordx4 v[156:157], off
	v_lshl_add_u64 v[156:157], v[232:233], 0, s[80:81]
	s_mov_b32 m0, s30
	s_nop 0
	global_load_lds_dwordx4 v[156:157], off
	v_lshl_add_u64 v[156:157], v[234:235], 0, s[80:81]
	s_add_i32 m0, s30, 0x2000
	s_nop 0
	global_load_lds_dwordx4 v[156:157], off
	v_lshl_add_u64 v[156:157], v[236:237], 0, s[80:81]
	s_mov_b32 m0, s51
	s_nop 0
	global_load_lds_dwordx4 v[156:157], off
	v_lshl_add_u64 v[156:157], v[238:239], 0, s[80:81]
	s_mov_b32 m0, s52
	s_nop 0
	global_load_lds_dwordx4 v[156:157], off
	ds_read_b128 v[180:183], v143 offset:49152
	ds_read_b128 v[184:187], v143 offset:50176
	ds_read_b128 v[188:191], v143 offset:51200
	ds_read_b128 v[192:195], v143 offset:52224
	ds_read_b128 v[214:217], v143 offset:53248
	ds_read_b128 v[218:221], v143 offset:54272
	ds_read_b128 v[222:225], v143 offset:55296
	ds_read_b128 v[226:229], v143 offset:56320
	s_waitcnt vmcnt(8)
	s_waitcnt lgkmcnt(0)
	s_barrier
	s_setprio 1
	s_waitcnt lgkmcnt(0)
	v_mfma_f32_16x16x32_bf16 v[60:63], v[144:147], v[180:183], v[60:63]
	v_mfma_f32_16x16x32_bf16 v[52:55], v[152:155], v[180:183], v[52:55]
	v_mfma_f32_16x16x32_bf16 v[44:47], v[144:147], v[188:191], v[44:47]
	v_mfma_f32_16x16x32_bf16 v[36:39], v[152:155], v[188:191], v[36:39]
	v_mfma_f32_16x16x32_bf16 v[28:31], v[144:147], v[214:217], v[28:31]
	v_mfma_f32_16x16x32_bf16 v[20:23], v[152:155], v[214:217], v[20:23]
	v_mfma_f32_16x16x32_bf16 v[12:15], v[144:147], v[222:225], v[12:15]
	v_mfma_f32_16x16x32_bf16 v[4:7], v[152:155], v[222:225], v[4:7]
	v_mfma_f32_16x16x32_bf16 v[60:63], v[148:151], v[184:187], v[60:63]
	v_mfma_f32_16x16x32_bf16 v[52:55], v[160:163], v[184:187], v[52:55]
	v_mfma_f32_16x16x32_bf16 v[44:47], v[148:151], v[192:195], v[44:47]
	v_mfma_f32_16x16x32_bf16 v[36:39], v[160:163], v[192:195], v[36:39]
	v_mfma_f32_16x16x32_bf16 v[28:31], v[148:151], v[218:221], v[28:31]
	v_mfma_f32_16x16x32_bf16 v[20:23], v[160:163], v[218:221], v[20:23]
	v_mfma_f32_16x16x32_bf16 v[12:15], v[148:151], v[226:229], v[12:15]
	v_mfma_f32_16x16x32_bf16 v[4:7], v[160:163], v[226:229], v[4:7]
	s_setprio 0
	s_setprio 1
	v_mfma_f32_16x16x32_bf16 v[56:59], v[164:167], v[180:183], v[56:59]
	v_mfma_f32_16x16x32_bf16 v[48:51], v[172:175], v[180:183], v[48:51]
	v_mfma_f32_16x16x32_bf16 v[40:43], v[164:167], v[188:191], v[40:43]
	v_mfma_f32_16x16x32_bf16 v[32:35], v[172:175], v[188:191], v[32:35]
	v_mfma_f32_16x16x32_bf16 v[24:27], v[164:167], v[214:217], v[24:27]
	v_mfma_f32_16x16x32_bf16 v[16:19], v[172:175], v[214:217], v[16:19]
	v_mfma_f32_16x16x32_bf16 v[8:11], v[164:167], v[222:225], v[8:11]
	v_mfma_f32_16x16x32_bf16 v[0:3], v[172:175], v[222:225], v[0:3]
	v_mfma_f32_16x16x32_bf16 v[56:59], v[168:171], v[184:187], v[56:59]
	v_mfma_f32_16x16x32_bf16 v[48:51], v[176:179], v[184:187], v[48:51]
	v_mfma_f32_16x16x32_bf16 v[40:43], v[168:171], v[192:195], v[40:43]
	v_mfma_f32_16x16x32_bf16 v[32:35], v[176:179], v[192:195], v[32:35]
	v_mfma_f32_16x16x32_bf16 v[24:27], v[168:171], v[218:221], v[24:27]
	v_mfma_f32_16x16x32_bf16 v[16:19], v[176:179], v[218:221], v[16:19]
	v_mfma_f32_16x16x32_bf16 v[8:11], v[168:171], v[226:229], v[8:11]
	v_mfma_f32_16x16x32_bf16 v[0:3], v[176:179], v[226:229], v[0:3]
	s_setprio 0
	s_barrier
	s_add_u32 s28, s28, 0x100
	s_addc_u32 s29, s29, 0
	s_add_u32 s60, s60, 0x100
	s_addc_u32 s61, s61, 0
	s_cmp_ge_i32 s62, s53
	s_mov_b32 s30, s62
	s_cbranch_scc0 .LBB0_511

.LBB0_596:
	s_add_i32 s63, s30, 2
	s_add_u32 s64, s28, 0x80
	s_addc_u32 s31, s29, 0
	s_add_i32 s66, 0, 0x10000
	s_cmp_eq_u32 s55, s30
	s_cselect_b32 s31, s7, s31
	s_cselect_b32 s30, s6, s64
	s_cselect_b32 s65, s27, s62
	s_cselect_b32 s64, s26, s61
	s_add_i32 s67, 0, 0x14000
	v_add_u32_e32 v152, s66, v164
	v_add_u32_e32 v156, s67, v164
	ds_read_b128 v[140:143], v152
	ds_read_b128 v[144:147], v152 offset:1024
	ds_read_b128 v[148:151], v152 offset:2048
	ds_read_b128 v[152:155], v152 offset:3072
	ds_read_b128 v[160:163], v156
	ds_read_b128 v[168:171], v156 offset:1024
	ds_read_b128 v[172:175], v156 offset:2048
	ds_read_b128 v[176:179], v156 offset:3072
	v_lshl_add_u64 v[156:157], s[28:29], 0, v[136:137]
	s_add_i32 m0, s46, 0xc000
	ds_read_b128 v[180:183], v166
	ds_read_b128 v[184:187], v166 offset:1024
	ds_read_b128 v[188:191], v166 offset:2048
	ds_read_b128 v[192:195], v166 offset:3072
	ds_read_b128 v[214:217], v166 offset:4096
	ds_read_b128 v[218:221], v166 offset:5120
	ds_read_b128 v[222:225], v166 offset:6144
	ds_read_b128 v[226:229], v166 offset:7168
	global_load_lds_dwordx4 v[156:157], off
	v_lshl_add_u64 v[156:157], s[28:29], 0, v[138:139]
	s_add_i32 m0, s46, 0xe000
	s_nop 0
	global_load_lds_dwordx4 v[156:157], off
	s_waitcnt vmcnt(8)
	s_waitcnt lgkmcnt(0)
	s_barrier
	s_setprio 1
	s_waitcnt lgkmcnt(0)
	v_mfma_f32_16x16x32_bf16 v[126:129], v[140:143], v[180:183], v[126:129]
	v_mfma_f32_16x16x32_bf16 v[122:125], v[148:151], v[180:183], v[122:125]
	v_mfma_f32_16x16x32_bf16 v[110:113], v[140:143], v[188:191], v[110:113]
	v_mfma_f32_16x16x32_bf16 v[106:109], v[148:151], v[188:191], v[106:109]
	v_mfma_f32_16x16x32_bf16 v[94:97], v[140:143], v[214:217], v[94:97]
	v_mfma_f32_16x16x32_bf16 v[88:91], v[148:151], v[214:217], v[88:91]
	v_mfma_f32_16x16x32_bf16 v[76:79], v[140:143], v[222:225], v[76:79]
	v_mfma_f32_16x16x32_bf16 v[72:75], v[148:151], v[222:225], v[72:75]
	v_mfma_f32_16x16x32_bf16 v[126:129], v[144:147], v[184:187], v[126:129]
	v_mfma_f32_16x16x32_bf16 v[122:125], v[152:155], v[184:187], v[122:125]
	v_mfma_f32_16x16x32_bf16 v[110:113], v[144:147], v[192:195], v[110:113]
	v_mfma_f32_16x16x32_bf16 v[106:109], v[152:155], v[192:195], v[106:109]
	v_mfma_f32_16x16x32_bf16 v[94:97], v[144:147], v[218:221], v[94:97]
	v_mfma_f32_16x16x32_bf16 v[88:91], v[152:155], v[218:221], v[88:91]
	v_mfma_f32_16x16x32_bf16 v[76:79], v[144:147], v[226:229], v[76:79]
	v_mfma_f32_16x16x32_bf16 v[72:75], v[152:155], v[226:229], v[72:75]
	s_setprio 0
	s_setprio 1
	v_mfma_f32_16x16x32_bf16 v[118:121], v[160:163], v[180:183], v[118:121]
	v_mfma_f32_16x16x32_bf16 v[114:117], v[172:175], v[180:183], v[114:117]
	v_mfma_f32_16x16x32_bf16 v[102:105], v[160:163], v[188:191], v[102:105]
	v_mfma_f32_16x16x32_bf16 v[98:101], v[172:175], v[188:191], v[98:101]
	v_mfma_f32_16x16x32_bf16 v[84:87], v[160:163], v[214:217], v[84:87]
	v_mfma_f32_16x16x32_bf16 v[80:83], v[172:175], v[214:217], v[80:83]
	v_mfma_f32_16x16x32_bf16 v[68:71], v[160:163], v[222:225], v[68:71]
	v_mfma_f32_16x16x32_bf16 v[64:67], v[172:175], v[222:225], v[64:67]
	v_mfma_f32_16x16x32_bf16 v[118:121], v[168:171], v[184:187], v[118:121]
	v_mfma_f32_16x16x32_bf16 v[114:117], v[176:179], v[184:187], v[114:117]
	v_mfma_f32_16x16x32_bf16 v[102:105], v[168:171], v[192:195], v[102:105]
	v_mfma_f32_16x16x32_bf16 v[98:101], v[176:179], v[192:195], v[98:101]
	v_mfma_f32_16x16x32_bf16 v[84:87], v[168:171], v[218:221], v[84:87]
	v_mfma_f32_16x16x32_bf16 v[80:83], v[176:179], v[218:221], v[80:83]
	v_mfma_f32_16x16x32_bf16 v[68:71], v[168:171], v[226:229], v[68:71]
	v_mfma_f32_16x16x32_bf16 v[64:67], v[176:179], v[226:229], v[64:67]
	s_setprio 0
	s_barrier
	s_add_i32 s66, s66, s41
	v_lshl_add_u64 v[156:157], s[64:65], 0, v[92:93]
	s_mov_b32 m0, s66
	global_load_lds_dwordx4 v[156:157], off
	s_add_i32 m0, s66, 0x2000
	v_lshl_add_u64 v[230:231], s[64:65], 0, v[134:135]
	s_add_u32 s64, s64, s10
	s_addc_u32 s65, s65, s11
	s_add_i32 s66, s67, s41
	global_load_lds_dwordx4 v[230:231], off
	v_lshl_add_u64 v[232:233], s[64:65], 0, v[92:93]
	s_mov_b32 m0, s66
	v_lshl_add_u64 v[234:235], s[64:65], 0, v[134:135]
	global_load_lds_dwordx4 v[232:233], off
	s_add_i32 m0, s66, 0x2000
	v_lshl_add_u64 v[236:237], s[30:31], 0, v[130:131]
	global_load_lds_dwordx4 v[234:235], off
	s_mov_b32 m0, s46
	v_lshl_add_u64 v[238:239], s[30:31], 0, v[132:133]
	global_load_lds_dwordx4 v[236:237], off
	s_mov_b32 m0, s47
	s_nop 0
	global_load_lds_dwordx4 v[238:239], off
	ds_read_b128 v[180:183], v166 offset:16384
	ds_read_b128 v[184:187], v166 offset:17408
	ds_read_b128 v[188:191], v166 offset:18432
	ds_read_b128 v[192:195], v166 offset:19456
	ds_read_b128 v[214:217], v166 offset:20480
	ds_read_b128 v[218:221], v166 offset:21504
	ds_read_b128 v[222:225], v166 offset:22528
	ds_read_b128 v[226:229], v166 offset:23552
	s_waitcnt vmcnt(8)
	s_waitcnt lgkmcnt(0)
	s_barrier
	s_setprio 1
	s_waitcnt lgkmcnt(0)
	v_mfma_f32_16x16x32_bf16 v[60:63], v[140:143], v[180:183], v[60:63]
	v_mfma_f32_16x16x32_bf16 v[56:59], v[148:151], v[180:183], v[56:59]
	v_mfma_f32_16x16x32_bf16 v[44:47], v[140:143], v[188:191], v[44:47]
	v_mfma_f32_16x16x32_bf16 v[40:43], v[148:151], v[188:191], v[40:43]
	v_mfma_f32_16x16x32_bf16 v[28:31], v[140:143], v[214:217], v[28:31]
	v_mfma_f32_16x16x32_bf16 v[24:27], v[148:151], v[214:217], v[24:27]
	v_mfma_f32_16x16x32_bf16 v[12:15], v[140:143], v[222:225], v[12:15]
	v_mfma_f32_16x16x32_bf16 v[8:11], v[148:151], v[222:225], v[8:11]
	v_mfma_f32_16x16x32_bf16 v[60:63], v[144:147], v[184:187], v[60:63]
	v_mfma_f32_16x16x32_bf16 v[56:59], v[152:155], v[184:187], v[56:59]
	v_mfma_f32_16x16x32_bf16 v[44:47], v[144:147], v[192:195], v[44:47]
	v_mfma_f32_16x16x32_bf16 v[40:43], v[152:155], v[192:195], v[40:43]
	v_mfma_f32_16x16x32_bf16 v[28:31], v[144:147], v[218:221], v[28:31]
	v_mfma_f32_16x16x32_bf16 v[24:27], v[152:155], v[218:221], v[24:27]
	v_mfma_f32_16x16x32_bf16 v[12:15], v[144:147], v[226:229], v[12:15]
	v_mfma_f32_16x16x32_bf16 v[8:11], v[152:155], v[226:229], v[8:11]
	s_setprio 0
	s_setprio 1
	v_mfma_f32_16x16x32_bf16 v[52:55], v[160:163], v[180:183], v[52:55]
	v_mfma_f32_16x16x32_bf16 v[48:51], v[172:175], v[180:183], v[48:51]
	v_mfma_f32_16x16x32_bf16 v[36:39], v[160:163], v[188:191], v[36:39]
	v_mfma_f32_16x16x32_bf16 v[32:35], v[172:175], v[188:191], v[32:35]
	v_mfma_f32_16x16x32_bf16 v[20:23], v[160:163], v[214:217], v[20:23]
	v_mfma_f32_16x16x32_bf16 v[16:19], v[172:175], v[214:217], v[16:19]
	v_mfma_f32_16x16x32_bf16 v[4:7], v[160:163], v[222:225], v[4:7]
	v_mfma_f32_16x16x32_bf16 v[0:3], v[172:175], v[222:225], v[0:3]
	v_mfma_f32_16x16x32_bf16 v[52:55], v[168:171], v[184:187], v[52:55]
	v_mfma_f32_16x16x32_bf16 v[48:51], v[176:179], v[184:187], v[48:51]
	v_mfma_f32_16x16x32_bf16 v[36:39], v[168:171], v[192:195], v[36:39]
	v_mfma_f32_16x16x32_bf16 v[32:35], v[176:179], v[192:195], v[32:35]
	v_mfma_f32_16x16x32_bf16 v[20:23], v[168:171], v[218:221], v[20:23]
	v_mfma_f32_16x16x32_bf16 v[16:19], v[176:179], v[218:221], v[16:19]
	v_mfma_f32_16x16x32_bf16 v[4:7], v[168:171], v[226:229], v[4:7]
	v_mfma_f32_16x16x32_bf16 v[0:3], v[176:179], v[226:229], v[0:3]
	s_setprio 0
	s_barrier
	s_add_i32 s64, 0, 0x18000
	s_add_i32 s65, 0, 0x1c000
	v_add_u32_e32 v152, s64, v164
	v_add_u32_e32 v167, s65, v164
	ds_read_b128 v[140:143], v152
	ds_read_b128 v[144:147], v152 offset:1024
	ds_read_b128 v[148:151], v152 offset:2048
	ds_read_b128 v[152:155], v152 offset:3072
	ds_read_b128 v[160:163], v167
	ds_read_b128 v[168:171], v167 offset:1024
	ds_read_b128 v[172:175], v167 offset:2048
	ds_read_b128 v[176:179], v167 offset:3072
	s_add_u32 s30, s30, s14
	s_addc_u32 s31, s31, s15
	s_mov_b32 m0, s48
	v_lshl_add_u64 v[240:241], s[30:31], 0, v[130:131]
	ds_read_b128 v[180:183], v166 offset:32768
	ds_read_b128 v[184:187], v166 offset:33792
	ds_read_b128 v[188:191], v166 offset:34816
	ds_read_b128 v[192:195], v166 offset:35840
	ds_read_b128 v[214:217], v166 offset:36864
	ds_read_b128 v[218:221], v166 offset:37888
	ds_read_b128 v[222:225], v166 offset:38912
	ds_read_b128 v[226:229], v166 offset:39936
	global_load_lds_dwordx4 v[240:241], off
	v_lshl_add_u64 v[240:241], s[30:31], 0, v[132:133]
	s_mov_b32 m0, s49
	s_nop 0
	global_load_lds_dwordx4 v[240:241], off
	s_waitcnt vmcnt(8)
	s_waitcnt lgkmcnt(0)
	s_barrier
	s_setprio 1
	s_waitcnt lgkmcnt(0)
	v_mfma_f32_16x16x32_bf16 v[126:129], v[140:143], v[180:183], v[126:129]
	v_mfma_f32_16x16x32_bf16 v[122:125], v[148:151], v[180:183], v[122:125]
	v_mfma_f32_16x16x32_bf16 v[110:113], v[140:143], v[188:191], v[110:113]
	v_mfma_f32_16x16x32_bf16 v[106:109], v[148:151], v[188:191], v[106:109]
	v_mfma_f32_16x16x32_bf16 v[94:97], v[140:143], v[214:217], v[94:97]
	v_mfma_f32_16x16x32_bf16 v[88:91], v[148:151], v[214:217], v[88:91]
	v_mfma_f32_16x16x32_bf16 v[76:79], v[140:143], v[222:225], v[76:79]
	v_mfma_f32_16x16x32_bf16 v[72:75], v[148:151], v[222:225], v[72:75]
	v_mfma_f32_16x16x32_bf16 v[126:129], v[144:147], v[184:187], v[126:129]
	v_mfma_f32_16x16x32_bf16 v[122:125], v[152:155], v[184:187], v[122:125]
	v_mfma_f32_16x16x32_bf16 v[110:113], v[144:147], v[192:195], v[110:113]
	v_mfma_f32_16x16x32_bf16 v[106:109], v[152:155], v[192:195], v[106:109]
	v_mfma_f32_16x16x32_bf16 v[94:97], v[144:147], v[218:221], v[94:97]
	v_mfma_f32_16x16x32_bf16 v[88:91], v[152:155], v[218:221], v[88:91]
	v_mfma_f32_16x16x32_bf16 v[76:79], v[144:147], v[226:229], v[76:79]
	v_mfma_f32_16x16x32_bf16 v[72:75], v[152:155], v[226:229], v[72:75]
	s_setprio 0
	s_setprio 1
	v_mfma_f32_16x16x32_bf16 v[118:121], v[160:163], v[180:183], v[118:121]
	v_mfma_f32_16x16x32_bf16 v[114:117], v[172:175], v[180:183], v[114:117]
	v_mfma_f32_16x16x32_bf16 v[102:105], v[160:163], v[188:191], v[102:105]
	v_mfma_f32_16x16x32_bf16 v[98:101], v[172:175], v[188:191], v[98:101]
	v_mfma_f32_16x16x32_bf16 v[84:87], v[160:163], v[214:217], v[84:87]
	v_mfma_f32_16x16x32_bf16 v[80:83], v[172:175], v[214:217], v[80:83]
	v_mfma_f32_16x16x32_bf16 v[68:71], v[160:163], v[222:225], v[68:71]
	v_mfma_f32_16x16x32_bf16 v[64:67], v[172:175], v[222:225], v[64:67]
	v_mfma_f32_16x16x32_bf16 v[118:121], v[168:171], v[184:187], v[118:121]
	v_mfma_f32_16x16x32_bf16 v[114:117], v[176:179], v[184:187], v[114:117]
	v_mfma_f32_16x16x32_bf16 v[102:105], v[168:171], v[192:195], v[102:105]
	v_mfma_f32_16x16x32_bf16 v[98:101], v[176:179], v[192:195], v[98:101]
	v_mfma_f32_16x16x32_bf16 v[84:87], v[168:171], v[218:221], v[84:87]
	v_mfma_f32_16x16x32_bf16 v[80:83], v[176:179], v[218:221], v[80:83]
	v_mfma_f32_16x16x32_bf16 v[68:71], v[168:171], v[226:229], v[68:71]
	v_mfma_f32_16x16x32_bf16 v[64:67], v[176:179], v[226:229], v[64:67]
	s_setprio 0
	s_barrier
	s_add_i32 s30, s64, s41
	v_lshl_add_u64 v[156:157], v[156:157], 0, s[80:81]
	s_mov_b32 m0, s30
	global_load_lds_dwordx4 v[156:157], off
	v_lshl_add_u64 v[156:157], v[230:231], 0, s[80:81]
	s_add_i32 m0, s30, 0x2000
	s_add_i32 s30, s65, s41
	global_load_lds_dwordx4 v[156:157], off
	v_lshl_add_u64 v[156:157], v[232:233], 0, s[80:81]
	s_mov_b32 m0, s30
	s_nop 0
	global_load_lds_dwordx4 v[156:157], off
	v_lshl_add_u64 v[156:157], v[234:235], 0, s[80:81]
	s_add_i32 m0, s30, 0x2000
	s_nop 0
	global_load_lds_dwordx4 v[156:157], off
	v_lshl_add_u64 v[156:157], v[236:237], 0, s[80:81]
	s_mov_b32 m0, s53
	s_nop 0
	global_load_lds_dwordx4 v[156:157], off
	v_lshl_add_u64 v[156:157], v[238:239], 0, s[80:81]
	s_mov_b32 m0, s54
	s_nop 0
	global_load_lds_dwordx4 v[156:157], off
	ds_read_b128 v[180:183], v166 offset:49152
	ds_read_b128 v[184:187], v166 offset:50176
	ds_read_b128 v[188:191], v166 offset:51200
	ds_read_b128 v[192:195], v166 offset:52224
	ds_read_b128 v[214:217], v166 offset:53248
	ds_read_b128 v[218:221], v166 offset:54272
	ds_read_b128 v[222:225], v166 offset:55296
	ds_read_b128 v[226:229], v166 offset:56320
	s_waitcnt vmcnt(8)
	s_waitcnt lgkmcnt(0)
	s_barrier
	s_setprio 1
	s_waitcnt lgkmcnt(0)
	v_mfma_f32_16x16x32_bf16 v[60:63], v[140:143], v[180:183], v[60:63]
	v_mfma_f32_16x16x32_bf16 v[56:59], v[148:151], v[180:183], v[56:59]
	v_mfma_f32_16x16x32_bf16 v[44:47], v[140:143], v[188:191], v[44:47]
	v_mfma_f32_16x16x32_bf16 v[40:43], v[148:151], v[188:191], v[40:43]
	v_mfma_f32_16x16x32_bf16 v[28:31], v[140:143], v[214:217], v[28:31]
	v_mfma_f32_16x16x32_bf16 v[24:27], v[148:151], v[214:217], v[24:27]
	v_mfma_f32_16x16x32_bf16 v[12:15], v[140:143], v[222:225], v[12:15]
	v_mfma_f32_16x16x32_bf16 v[8:11], v[148:151], v[222:225], v[8:11]
	v_mfma_f32_16x16x32_bf16 v[60:63], v[144:147], v[184:187], v[60:63]
	v_mfma_f32_16x16x32_bf16 v[56:59], v[152:155], v[184:187], v[56:59]
	v_mfma_f32_16x16x32_bf16 v[44:47], v[144:147], v[192:195], v[44:47]
	v_mfma_f32_16x16x32_bf16 v[40:43], v[152:155], v[192:195], v[40:43]
	v_mfma_f32_16x16x32_bf16 v[28:31], v[144:147], v[218:221], v[28:31]
	v_mfma_f32_16x16x32_bf16 v[24:27], v[152:155], v[218:221], v[24:27]
	v_mfma_f32_16x16x32_bf16 v[12:15], v[144:147], v[226:229], v[12:15]
	v_mfma_f32_16x16x32_bf16 v[8:11], v[152:155], v[226:229], v[8:11]
	s_setprio 0
	s_setprio 1
	v_mfma_f32_16x16x32_bf16 v[52:55], v[160:163], v[180:183], v[52:55]
	v_mfma_f32_16x16x32_bf16 v[48:51], v[172:175], v[180:183], v[48:51]
	v_mfma_f32_16x16x32_bf16 v[36:39], v[160:163], v[188:191], v[36:39]
	v_mfma_f32_16x16x32_bf16 v[32:35], v[172:175], v[188:191], v[32:35]
	v_mfma_f32_16x16x32_bf16 v[20:23], v[160:163], v[214:217], v[20:23]
	v_mfma_f32_16x16x32_bf16 v[16:19], v[172:175], v[214:217], v[16:19]
	v_mfma_f32_16x16x32_bf16 v[4:7], v[160:163], v[222:225], v[4:7]
	v_mfma_f32_16x16x32_bf16 v[0:3], v[172:175], v[222:225], v[0:3]
	v_mfma_f32_16x16x32_bf16 v[52:55], v[168:171], v[184:187], v[52:55]
	v_mfma_f32_16x16x32_bf16 v[48:51], v[176:179], v[184:187], v[48:51]
	v_mfma_f32_16x16x32_bf16 v[36:39], v[168:171], v[192:195], v[36:39]
	v_mfma_f32_16x16x32_bf16 v[32:35], v[176:179], v[192:195], v[32:35]
	v_mfma_f32_16x16x32_bf16 v[20:23], v[168:171], v[218:221], v[20:23]
	v_mfma_f32_16x16x32_bf16 v[16:19], v[176:179], v[218:221], v[16:19]
	v_mfma_f32_16x16x32_bf16 v[4:7], v[168:171], v[226:229], v[4:7]
	v_mfma_f32_16x16x32_bf16 v[0:3], v[176:179], v[226:229], v[0:3]
	s_setprio 0
	s_barrier
	s_add_u32 s28, s28, 0x100
	s_addc_u32 s29, s29, 0
	s_add_u32 s61, s61, 0x100
	s_addc_u32 s62, s62, 0
	s_cmp_ge_i32 s63, s52
	s_mov_b32 s30, s63
	s_cbranch_scc0 .LBB0_596
	s_movk_i32 s67, 0x4000

.LBB0_685:
	s_add_i32 s36, s10, 2
	s_add_u32 s37, s8, 0x80
	s_addc_u32 s11, s9, 0
	s_add_i32 s40, 0, 0x10000
	s_cmp_eq_u32 s71, s10
	s_cselect_b32 s11, s29, s11
	s_cselect_b32 s10, s28, s37
	v_add_u32_e32 v92, s40, v141
	s_cselect_b32 s39, s31, s35
	s_cselect_b32 s38, s30, s34
	s_add_i32 s37, 0, 0x14000
	ds_read_b128 v[152:155], v92
	ds_read_b128 v[160:163], v92 offset:1024
	ds_read_b128 v[164:167], v92 offset:2048
	ds_read_b128 v[168:171], v92 offset:3072
	v_add_u32_e32 v92, s37, v141
	ds_read_b128 v[172:175], v92
	ds_read_b128 v[176:179], v92 offset:1024
	ds_read_b128 v[180:183], v92 offset:2048
	ds_read_b128 v[184:187], v92 offset:3072
	v_lshl_add_u64 v[156:157], s[8:9], 0, v[148:149]
	s_add_i32 m0, s54, 0xc000
	ds_read_b128 v[188:191], v143
	ds_read_b128 v[192:195], v143 offset:1024
	ds_read_b128 v[214:217], v143 offset:2048
	ds_read_b128 v[218:221], v143 offset:3072
	ds_read_b128 v[222:225], v143 offset:4096
	ds_read_b128 v[226:229], v143 offset:5120
	ds_read_b128 v[230:233], v143 offset:6144
	ds_read_b128 v[234:237], v143 offset:7168
	global_load_lds_dwordx4 v[156:157], off
	v_lshl_add_u64 v[156:157], s[8:9], 0, v[150:151]
	s_add_i32 m0, s54, 0xe000
	s_nop 0
	global_load_lds_dwordx4 v[156:157], off
	s_waitcnt vmcnt(8)
	s_waitcnt lgkmcnt(0)
	s_barrier
	s_setprio 1
	s_waitcnt lgkmcnt(0)
	v_mfma_f32_16x16x32_bf16 v[126:129], v[152:155], v[188:191], v[126:129]
	v_mfma_f32_16x16x32_bf16 v[122:125], v[164:167], v[188:191], v[122:125]
	v_mfma_f32_16x16x32_bf16 v[118:121], v[152:155], v[214:217], v[118:121]
	v_mfma_f32_16x16x32_bf16 v[114:117], v[164:167], v[214:217], v[114:117]
	v_mfma_f32_16x16x32_bf16 v[110:113], v[152:155], v[222:225], v[110:113]
	v_mfma_f32_16x16x32_bf16 v[106:109], v[164:167], v[222:225], v[106:109]
	v_mfma_f32_16x16x32_bf16 v[102:105], v[152:155], v[230:233], v[102:105]
	v_mfma_f32_16x16x32_bf16 v[98:101], v[164:167], v[230:233], v[98:101]
	v_mfma_f32_16x16x32_bf16 v[126:129], v[160:163], v[192:195], v[126:129]
	v_mfma_f32_16x16x32_bf16 v[122:125], v[168:171], v[192:195], v[122:125]
	v_mfma_f32_16x16x32_bf16 v[118:121], v[160:163], v[218:221], v[118:121]
	v_mfma_f32_16x16x32_bf16 v[114:117], v[168:171], v[218:221], v[114:117]
	v_mfma_f32_16x16x32_bf16 v[110:113], v[160:163], v[226:229], v[110:113]
	v_mfma_f32_16x16x32_bf16 v[106:109], v[168:171], v[226:229], v[106:109]
	v_mfma_f32_16x16x32_bf16 v[102:105], v[160:163], v[234:237], v[102:105]
	v_mfma_f32_16x16x32_bf16 v[98:101], v[168:171], v[234:237], v[98:101]
	s_setprio 0
	s_setprio 1
	v_mfma_f32_16x16x32_bf16 v[60:63], v[172:175], v[188:191], v[60:63]
	v_mfma_f32_16x16x32_bf16 v[56:59], v[180:183], v[188:191], v[56:59]
	v_mfma_f32_16x16x32_bf16 v[52:55], v[172:175], v[214:217], v[52:55]
	v_mfma_f32_16x16x32_bf16 v[48:51], v[180:183], v[214:217], v[48:51]
	v_mfma_f32_16x16x32_bf16 v[44:47], v[172:175], v[222:225], v[44:47]
	v_mfma_f32_16x16x32_bf16 v[40:43], v[180:183], v[222:225], v[40:43]
	v_mfma_f32_16x16x32_bf16 v[36:39], v[172:175], v[230:233], v[36:39]
	v_mfma_f32_16x16x32_bf16 v[32:35], v[180:183], v[230:233], v[32:35]
	v_mfma_f32_16x16x32_bf16 v[60:63], v[176:179], v[192:195], v[60:63]
	v_mfma_f32_16x16x32_bf16 v[56:59], v[184:187], v[192:195], v[56:59]
	v_mfma_f32_16x16x32_bf16 v[52:55], v[176:179], v[218:221], v[52:55]
	v_mfma_f32_16x16x32_bf16 v[48:51], v[184:187], v[218:221], v[48:51]
	v_mfma_f32_16x16x32_bf16 v[44:47], v[176:179], v[226:229], v[44:47]
	v_mfma_f32_16x16x32_bf16 v[40:43], v[184:187], v[226:229], v[40:43]
	v_mfma_f32_16x16x32_bf16 v[36:39], v[176:179], v[234:237], v[36:39]
	v_mfma_f32_16x16x32_bf16 v[32:35], v[184:187], v[234:237], v[32:35]
	s_setprio 0
	s_barrier
	s_add_i32 s40, s40, s53
	v_lshl_add_u64 v[156:157], s[38:39], 0, v[132:133]
	s_mov_b32 m0, s40
	global_load_lds_dwordx4 v[156:157], off
	s_add_i32 m0, s40, 0x2000
	v_lshl_add_u64 v[238:239], s[38:39], 0, v[136:137]
	s_add_u32 s38, s38, s12
	s_addc_u32 s39, s39, s13
	s_add_i32 s37, s37, s53
	global_load_lds_dwordx4 v[238:239], off
	v_lshl_add_u64 v[240:241], s[38:39], 0, v[132:133]
	s_mov_b32 m0, s37
	v_lshl_add_u64 v[242:243], s[38:39], 0, v[136:137]
	global_load_lds_dwordx4 v[240:241], off
	s_add_i32 m0, s37, 0x2000
	v_lshl_add_u64 v[244:245], s[10:11], 0, v[130:131]
	global_load_lds_dwordx4 v[242:243], off
	s_mov_b32 m0, s54
	v_lshl_add_u64 v[246:247], s[10:11], 0, v[134:135]
	global_load_lds_dwordx4 v[244:245], off
	s_mov_b32 m0, s55
	s_nop 0
	global_load_lds_dwordx4 v[246:247], off
	ds_read_b128 v[188:191], v143 offset:16384
	ds_read_b128 v[192:195], v143 offset:17408
	ds_read_b128 v[214:217], v143 offset:18432
	ds_read_b128 v[218:221], v143 offset:19456
	ds_read_b128 v[222:225], v143 offset:20480
	ds_read_b128 v[226:229], v143 offset:21504
	ds_read_b128 v[230:233], v143 offset:22528
	ds_read_b128 v[234:237], v143 offset:23552
	s_waitcnt vmcnt(8)
	s_waitcnt lgkmcnt(0)
	s_barrier
	s_setprio 1
	s_waitcnt lgkmcnt(0)
	v_mfma_f32_16x16x32_bf16 v[94:97], v[152:155], v[188:191], v[94:97]
	v_mfma_f32_16x16x32_bf16 v[88:91], v[164:167], v[188:191], v[88:91]
	v_mfma_f32_16x16x32_bf16 v[84:87], v[152:155], v[214:217], v[84:87]
	v_mfma_f32_16x16x32_bf16 v[80:83], v[164:167], v[214:217], v[80:83]
	v_mfma_f32_16x16x32_bf16 v[76:79], v[152:155], v[222:225], v[76:79]
	v_mfma_f32_16x16x32_bf16 v[72:75], v[164:167], v[222:225], v[72:75]
	v_mfma_f32_16x16x32_bf16 v[68:71], v[152:155], v[230:233], v[68:71]
	v_mfma_f32_16x16x32_bf16 v[64:67], v[164:167], v[230:233], v[64:67]
	v_mfma_f32_16x16x32_bf16 v[94:97], v[160:163], v[192:195], v[94:97]
	v_mfma_f32_16x16x32_bf16 v[88:91], v[168:171], v[192:195], v[88:91]
	v_mfma_f32_16x16x32_bf16 v[84:87], v[160:163], v[218:221], v[84:87]
	v_mfma_f32_16x16x32_bf16 v[80:83], v[168:171], v[218:221], v[80:83]
	v_mfma_f32_16x16x32_bf16 v[76:79], v[160:163], v[226:229], v[76:79]
	v_mfma_f32_16x16x32_bf16 v[72:75], v[168:171], v[226:229], v[72:75]
	v_mfma_f32_16x16x32_bf16 v[68:71], v[160:163], v[234:237], v[68:71]
	v_mfma_f32_16x16x32_bf16 v[64:67], v[168:171], v[234:237], v[64:67]
	s_setprio 0
	s_setprio 1
	v_mfma_f32_16x16x32_bf16 v[28:31], v[172:175], v[188:191], v[28:31]
	v_mfma_f32_16x16x32_bf16 v[24:27], v[180:183], v[188:191], v[24:27]
	v_mfma_f32_16x16x32_bf16 v[20:23], v[172:175], v[214:217], v[20:23]
	v_mfma_f32_16x16x32_bf16 v[16:19], v[180:183], v[214:217], v[16:19]
	v_mfma_f32_16x16x32_bf16 v[12:15], v[172:175], v[222:225], v[12:15]
	v_mfma_f32_16x16x32_bf16 v[8:11], v[180:183], v[222:225], v[8:11]
	v_mfma_f32_16x16x32_bf16 v[4:7], v[172:175], v[230:233], v[4:7]
	v_mfma_f32_16x16x32_bf16 v[0:3], v[180:183], v[230:233], v[0:3]
	v_mfma_f32_16x16x32_bf16 v[28:31], v[176:179], v[192:195], v[28:31]
	v_mfma_f32_16x16x32_bf16 v[24:27], v[184:187], v[192:195], v[24:27]
	v_mfma_f32_16x16x32_bf16 v[20:23], v[176:179], v[218:221], v[20:23]
	v_mfma_f32_16x16x32_bf16 v[16:19], v[184:187], v[218:221], v[16:19]
	v_mfma_f32_16x16x32_bf16 v[12:15], v[176:179], v[226:229], v[12:15]
	v_mfma_f32_16x16x32_bf16 v[8:11], v[184:187], v[226:229], v[8:11]
	v_mfma_f32_16x16x32_bf16 v[4:7], v[176:179], v[234:237], v[4:7]
	v_mfma_f32_16x16x32_bf16 v[0:3], v[184:187], v[234:237], v[0:3]
	s_setprio 0
	s_barrier
	s_add_i32 s37, 0, 0x18000
	v_add_u32_e32 v92, s37, v141
	s_add_i32 s38, 0, 0x1c000
	ds_read_b128 v[152:155], v92
	ds_read_b128 v[160:163], v92 offset:1024
	ds_read_b128 v[164:167], v92 offset:2048
	ds_read_b128 v[168:171], v92 offset:3072
	v_add_u32_e32 v92, s38, v141
	ds_read_b128 v[172:175], v92
	ds_read_b128 v[176:179], v92 offset:1024
	ds_read_b128 v[180:183], v92 offset:2048
	ds_read_b128 v[184:187], v92 offset:3072
	s_add_u32 s10, s10, s16
	s_addc_u32 s11, s11, s17
	s_mov_b32 m0, s56
	v_lshl_add_u64 v[248:249], s[10:11], 0, v[130:131]
	ds_read_b128 v[188:191], v143 offset:32768
	ds_read_b128 v[192:195], v143 offset:33792
	ds_read_b128 v[214:217], v143 offset:34816
	ds_read_b128 v[218:221], v143 offset:35840
	ds_read_b128 v[222:225], v143 offset:36864
	ds_read_b128 v[226:229], v143 offset:37888
	ds_read_b128 v[230:233], v143 offset:38912
	ds_read_b128 v[234:237], v143 offset:39936
	global_load_lds_dwordx4 v[248:249], off
	v_lshl_add_u64 v[248:249], s[10:11], 0, v[134:135]
	s_mov_b32 m0, s57
	s_nop 0
	global_load_lds_dwordx4 v[248:249], off
	s_waitcnt vmcnt(8)
	s_waitcnt lgkmcnt(0)
	s_barrier
	s_setprio 1
	s_waitcnt lgkmcnt(0)
	v_mfma_f32_16x16x32_bf16 v[126:129], v[152:155], v[188:191], v[126:129]
	v_mfma_f32_16x16x32_bf16 v[122:125], v[164:167], v[188:191], v[122:125]
	v_mfma_f32_16x16x32_bf16 v[118:121], v[152:155], v[214:217], v[118:121]
	v_mfma_f32_16x16x32_bf16 v[114:117], v[164:167], v[214:217], v[114:117]
	v_mfma_f32_16x16x32_bf16 v[110:113], v[152:155], v[222:225], v[110:113]
	v_mfma_f32_16x16x32_bf16 v[106:109], v[164:167], v[222:225], v[106:109]
	v_mfma_f32_16x16x32_bf16 v[102:105], v[152:155], v[230:233], v[102:105]
	v_mfma_f32_16x16x32_bf16 v[98:101], v[164:167], v[230:233], v[98:101]
	v_mfma_f32_16x16x32_bf16 v[126:129], v[160:163], v[192:195], v[126:129]
	v_mfma_f32_16x16x32_bf16 v[122:125], v[168:171], v[192:195], v[122:125]
	v_mfma_f32_16x16x32_bf16 v[118:121], v[160:163], v[218:221], v[118:121]
	v_mfma_f32_16x16x32_bf16 v[114:117], v[168:171], v[218:221], v[114:117]
	v_mfma_f32_16x16x32_bf16 v[110:113], v[160:163], v[226:229], v[110:113]
	v_mfma_f32_16x16x32_bf16 v[106:109], v[168:171], v[226:229], v[106:109]
	v_mfma_f32_16x16x32_bf16 v[102:105], v[160:163], v[234:237], v[102:105]
	v_mfma_f32_16x16x32_bf16 v[98:101], v[168:171], v[234:237], v[98:101]
	s_setprio 0
	s_setprio 1
	v_mfma_f32_16x16x32_bf16 v[60:63], v[172:175], v[188:191], v[60:63]
	v_mfma_f32_16x16x32_bf16 v[56:59], v[180:183], v[188:191], v[56:59]
	v_mfma_f32_16x16x32_bf16 v[52:55], v[172:175], v[214:217], v[52:55]
	v_mfma_f32_16x16x32_bf16 v[48:51], v[180:183], v[214:217], v[48:51]
	v_mfma_f32_16x16x32_bf16 v[44:47], v[172:175], v[222:225], v[44:47]
	v_mfma_f32_16x16x32_bf16 v[40:43], v[180:183], v[222:225], v[40:43]
	v_mfma_f32_16x16x32_bf16 v[36:39], v[172:175], v[230:233], v[36:39]
	v_mfma_f32_16x16x32_bf16 v[32:35], v[180:183], v[230:233], v[32:35]
	v_mfma_f32_16x16x32_bf16 v[60:63], v[176:179], v[192:195], v[60:63]
	v_mfma_f32_16x16x32_bf16 v[56:59], v[184:187], v[192:195], v[56:59]
	v_mfma_f32_16x16x32_bf16 v[52:55], v[176:179], v[218:221], v[52:55]
	v_mfma_f32_16x16x32_bf16 v[48:51], v[184:187], v[218:221], v[48:51]
	v_mfma_f32_16x16x32_bf16 v[44:47], v[176:179], v[226:229], v[44:47]
	v_mfma_f32_16x16x32_bf16 v[40:43], v[184:187], v[226:229], v[40:43]
	v_mfma_f32_16x16x32_bf16 v[36:39], v[176:179], v[234:237], v[36:39]
	v_mfma_f32_16x16x32_bf16 v[32:35], v[184:187], v[234:237], v[32:35]
	s_setprio 0
	s_barrier
	s_add_i32 s10, s37, s53
	v_lshl_add_u64 v[156:157], v[156:157], 0, s[80:81]
	s_mov_b32 m0, s10
	global_load_lds_dwordx4 v[156:157], off
	v_lshl_add_u64 v[156:157], v[238:239], 0, s[80:81]
	s_add_i32 m0, s10, 0x2000
	s_add_i32 s10, s38, s53
	global_load_lds_dwordx4 v[156:157], off
	v_lshl_add_u64 v[156:157], v[240:241], 0, s[80:81]
	s_mov_b32 m0, s10
	s_nop 0
	global_load_lds_dwordx4 v[156:157], off
	v_lshl_add_u64 v[156:157], v[242:243], 0, s[80:81]
	s_add_i32 m0, s10, 0x2000
	s_nop 0
	global_load_lds_dwordx4 v[156:157], off
	v_lshl_add_u64 v[156:157], v[244:245], 0, s[80:81]
	s_mov_b32 m0, s69
	s_nop 0
	global_load_lds_dwordx4 v[156:157], off
	v_lshl_add_u64 v[156:157], v[246:247], 0, s[80:81]
	s_mov_b32 m0, s70
	s_nop 0
	global_load_lds_dwordx4 v[156:157], off
	ds_read_b128 v[188:191], v143 offset:49152
	ds_read_b128 v[192:195], v143 offset:50176
	ds_read_b128 v[214:217], v143 offset:51200
	ds_read_b128 v[218:221], v143 offset:52224
	ds_read_b128 v[222:225], v143 offset:53248
	ds_read_b128 v[226:229], v143 offset:54272
	ds_read_b128 v[230:233], v143 offset:55296
	ds_read_b128 v[234:237], v143 offset:56320
	s_waitcnt vmcnt(8)
	s_waitcnt lgkmcnt(0)
	s_barrier
	s_setprio 1
	s_waitcnt lgkmcnt(0)
	v_mfma_f32_16x16x32_bf16 v[94:97], v[152:155], v[188:191], v[94:97]
	v_mfma_f32_16x16x32_bf16 v[88:91], v[164:167], v[188:191], v[88:91]
	v_mfma_f32_16x16x32_bf16 v[84:87], v[152:155], v[214:217], v[84:87]
	v_mfma_f32_16x16x32_bf16 v[80:83], v[164:167], v[214:217], v[80:83]
	v_mfma_f32_16x16x32_bf16 v[76:79], v[152:155], v[222:225], v[76:79]
	v_mfma_f32_16x16x32_bf16 v[72:75], v[164:167], v[222:225], v[72:75]
	v_mfma_f32_16x16x32_bf16 v[68:71], v[152:155], v[230:233], v[68:71]
	v_mfma_f32_16x16x32_bf16 v[64:67], v[164:167], v[230:233], v[64:67]
	v_mfma_f32_16x16x32_bf16 v[94:97], v[160:163], v[192:195], v[94:97]
	v_mfma_f32_16x16x32_bf16 v[88:91], v[168:171], v[192:195], v[88:91]
	v_mfma_f32_16x16x32_bf16 v[84:87], v[160:163], v[218:221], v[84:87]
	v_mfma_f32_16x16x32_bf16 v[80:83], v[168:171], v[218:221], v[80:83]
	v_mfma_f32_16x16x32_bf16 v[76:79], v[160:163], v[226:229], v[76:79]
	v_mfma_f32_16x16x32_bf16 v[72:75], v[168:171], v[226:229], v[72:75]
	v_mfma_f32_16x16x32_bf16 v[68:71], v[160:163], v[234:237], v[68:71]
	v_mfma_f32_16x16x32_bf16 v[64:67], v[168:171], v[234:237], v[64:67]
	s_setprio 0
	s_setprio 1
	v_mfma_f32_16x16x32_bf16 v[28:31], v[172:175], v[188:191], v[28:31]
	v_mfma_f32_16x16x32_bf16 v[24:27], v[180:183], v[188:191], v[24:27]
	v_mfma_f32_16x16x32_bf16 v[20:23], v[172:175], v[214:217], v[20:23]
	v_mfma_f32_16x16x32_bf16 v[16:19], v[180:183], v[214:217], v[16:19]
	v_mfma_f32_16x16x32_bf16 v[12:15], v[172:175], v[222:225], v[12:15]
	v_mfma_f32_16x16x32_bf16 v[8:11], v[180:183], v[222:225], v[8:11]
	v_mfma_f32_16x16x32_bf16 v[4:7], v[172:175], v[230:233], v[4:7]
	v_mfma_f32_16x16x32_bf16 v[0:3], v[180:183], v[230:233], v[0:3]
	v_mfma_f32_16x16x32_bf16 v[28:31], v[176:179], v[192:195], v[28:31]
	v_mfma_f32_16x16x32_bf16 v[24:27], v[184:187], v[192:195], v[24:27]
	v_mfma_f32_16x16x32_bf16 v[20:23], v[176:179], v[218:221], v[20:23]
	v_mfma_f32_16x16x32_bf16 v[16:19], v[184:187], v[218:221], v[16:19]
	v_mfma_f32_16x16x32_bf16 v[12:15], v[176:179], v[226:229], v[12:15]
	v_mfma_f32_16x16x32_bf16 v[8:11], v[184:187], v[226:229], v[8:11]
	v_mfma_f32_16x16x32_bf16 v[4:7], v[176:179], v[234:237], v[4:7]
	v_mfma_f32_16x16x32_bf16 v[0:3], v[184:187], v[234:237], v[0:3]
	s_setprio 0
	s_barrier
	s_add_u32 s8, s8, 0x100
	s_addc_u32 s9, s9, 0
	s_add_u32 s34, s34, 0x100
	s_addc_u32 s35, s35, 0
	s_cmp_ge_i32 s36, s68
	s_mov_b32 s10, s36
	s_cbranch_scc0 .LBB0_685

.LBB0_962:
	s_add_i32 s63, s24, 2
	s_add_u32 s64, s26, 0x80
	s_addc_u32 s25, s27, 0
	s_add_i32 s66, 0, 0x10000
	v_add_u32_e32 v79, s66, v77
	ds_read_b128 v[80:83], v79
	ds_read_b128 v[84:87], v79 offset:1024
	ds_read_b128 v[88:91], v79 offset:2048
	ds_read_b128 v[94:97], v79 offset:3072
	s_cmp_eq_u32 s57, s24
	s_cselect_b32 s24, s6, s64
	s_cselect_b32 s25, s7, s25
	s_cselect_b32 s65, s23, s62
	s_cselect_b32 s64, s22, s61
	v_lshl_add_u64 v[130:131], s[26:27], 0, v[72:73]
	s_add_i32 m0, s45, 0xc000
	ds_read_b128 v[98:101], v78
	ds_read_b128 v[102:105], v78 offset:1024
	ds_read_b128 v[106:109], v78 offset:2048
	ds_read_b128 v[110:113], v78 offset:3072
	ds_read_b128 v[114:117], v78 offset:4096
	ds_read_b128 v[118:121], v78 offset:5120
	ds_read_b128 v[122:125], v78 offset:6144
	ds_read_b128 v[126:129], v78 offset:7168
	global_load_lds_dwordx4 v[130:131], off
	v_lshl_add_u64 v[130:131], s[26:27], 0, v[74:75]
	s_add_i32 m0, s45, 0xe000
	s_nop 0
	global_load_lds_dwordx4 v[130:131], off
	s_waitcnt vmcnt(8)
	s_waitcnt lgkmcnt(0)
	s_barrier
	s_setprio 1
	s_waitcnt lgkmcnt(0)
	v_mfma_f32_16x16x32_bf16 v[60:63], v[80:83], v[98:101], v[60:63]
	v_mfma_f32_16x16x32_bf16 v[56:59], v[88:91], v[98:101], v[56:59]
	v_mfma_f32_16x16x32_bf16 v[52:55], v[80:83], v[106:109], v[52:55]
	v_mfma_f32_16x16x32_bf16 v[48:51], v[88:91], v[106:109], v[48:51]
	v_mfma_f32_16x16x32_bf16 v[44:47], v[80:83], v[114:117], v[44:47]
	v_mfma_f32_16x16x32_bf16 v[40:43], v[88:91], v[114:117], v[40:43]
	v_mfma_f32_16x16x32_bf16 v[36:39], v[80:83], v[122:125], v[36:39]
	v_mfma_f32_16x16x32_bf16 v[32:35], v[88:91], v[122:125], v[32:35]
	v_mfma_f32_16x16x32_bf16 v[60:63], v[84:87], v[102:105], v[60:63]
	v_mfma_f32_16x16x32_bf16 v[56:59], v[94:97], v[102:105], v[56:59]
	v_mfma_f32_16x16x32_bf16 v[52:55], v[84:87], v[110:113], v[52:55]
	v_mfma_f32_16x16x32_bf16 v[48:51], v[94:97], v[110:113], v[48:51]
	v_mfma_f32_16x16x32_bf16 v[44:47], v[84:87], v[118:121], v[44:47]
	v_mfma_f32_16x16x32_bf16 v[40:43], v[94:97], v[118:121], v[40:43]
	v_mfma_f32_16x16x32_bf16 v[36:39], v[84:87], v[126:129], v[36:39]
	v_mfma_f32_16x16x32_bf16 v[32:35], v[94:97], v[126:129], v[32:35]
	s_setprio 0
	s_setprio 1
	s_setprio 0
	s_barrier
	s_add_i32 s66, s66, s40
	v_lshl_add_u64 v[130:131], s[64:65], 0, v[92:93]
	s_mov_b32 m0, s66
	global_load_lds_dwordx4 v[130:131], off
	s_add_i32 m0, s66, 0x2000
	v_lshl_add_u64 v[132:133], s[64:65], 0, v[68:69]
	s_add_u32 s64, s64, s8
	s_addc_u32 s65, s65, s9
	global_load_lds_dwordx4 v[132:133], off
	v_lshl_add_u64 v[134:135], s[64:65], 0, v[92:93]
	s_mov_b32 m0, s46
	v_lshl_add_u64 v[136:137], s[64:65], 0, v[68:69]
	global_load_lds_dwordx4 v[134:135], off
	s_mov_b32 m0, s47
	v_lshl_add_u64 v[138:139], s[24:25], 0, v[64:65]
	global_load_lds_dwordx4 v[136:137], off
	s_mov_b32 m0, s45
	v_lshl_add_u64 v[140:141], s[24:25], 0, v[66:67]
	global_load_lds_dwordx4 v[138:139], off
	s_mov_b32 m0, s48
	s_nop 0
	global_load_lds_dwordx4 v[140:141], off
	ds_read_b128 v[98:101], v78 offset:16384
	ds_read_b128 v[102:105], v78 offset:17408
	ds_read_b128 v[106:109], v78 offset:18432
	ds_read_b128 v[110:113], v78 offset:19456
	ds_read_b128 v[114:117], v78 offset:20480
	ds_read_b128 v[118:121], v78 offset:21504
	ds_read_b128 v[122:125], v78 offset:22528
	ds_read_b128 v[126:129], v78 offset:23552
	s_waitcnt vmcnt(8)
	s_waitcnt lgkmcnt(0)
	s_barrier
	s_setprio 1
	s_waitcnt lgkmcnt(0)
	v_mfma_f32_16x16x32_bf16 v[28:31], v[80:83], v[98:101], v[28:31]
	v_mfma_f32_16x16x32_bf16 v[24:27], v[88:91], v[98:101], v[24:27]
	v_mfma_f32_16x16x32_bf16 v[20:23], v[80:83], v[106:109], v[20:23]
	v_mfma_f32_16x16x32_bf16 v[16:19], v[88:91], v[106:109], v[16:19]
	v_mfma_f32_16x16x32_bf16 v[12:15], v[80:83], v[114:117], v[12:15]
	v_mfma_f32_16x16x32_bf16 v[8:11], v[88:91], v[114:117], v[8:11]
	v_mfma_f32_16x16x32_bf16 v[4:7], v[80:83], v[122:125], v[4:7]
	v_mfma_f32_16x16x32_bf16 v[0:3], v[88:91], v[122:125], v[0:3]
	v_mfma_f32_16x16x32_bf16 v[28:31], v[84:87], v[102:105], v[28:31]
	v_mfma_f32_16x16x32_bf16 v[24:27], v[94:97], v[102:105], v[24:27]
	v_mfma_f32_16x16x32_bf16 v[20:23], v[84:87], v[110:113], v[20:23]
	v_mfma_f32_16x16x32_bf16 v[16:19], v[94:97], v[110:113], v[16:19]
	v_mfma_f32_16x16x32_bf16 v[12:15], v[84:87], v[118:121], v[12:15]
	v_mfma_f32_16x16x32_bf16 v[8:11], v[94:97], v[118:121], v[8:11]
	v_mfma_f32_16x16x32_bf16 v[4:7], v[84:87], v[126:129], v[4:7]
	v_mfma_f32_16x16x32_bf16 v[0:3], v[94:97], v[126:129], v[0:3]
	s_setprio 0
	s_setprio 1
	s_setprio 0
	s_barrier
	s_add_i32 s64, 0, 0x18000
	v_add_u32_e32 v79, s64, v77
	ds_read_b128 v[80:83], v79
	ds_read_b128 v[84:87], v79 offset:1024
	ds_read_b128 v[88:91], v79 offset:2048
	ds_read_b128 v[94:97], v79 offset:3072
	s_add_u32 s24, s24, s12
	s_addc_u32 s25, s25, s13
	s_mov_b32 m0, s49
	v_lshl_add_u64 v[142:143], s[24:25], 0, v[64:65]
	ds_read_b128 v[98:101], v78 offset:32768
	ds_read_b128 v[102:105], v78 offset:33792
	ds_read_b128 v[106:109], v78 offset:34816
	ds_read_b128 v[110:113], v78 offset:35840
	ds_read_b128 v[114:117], v78 offset:36864
	ds_read_b128 v[118:121], v78 offset:37888
	ds_read_b128 v[122:125], v78 offset:38912
	ds_read_b128 v[126:129], v78 offset:39936
	global_load_lds_dwordx4 v[142:143], off
	v_lshl_add_u64 v[142:143], s[24:25], 0, v[66:67]
	s_mov_b32 m0, s50
	s_nop 0
	global_load_lds_dwordx4 v[142:143], off
	s_waitcnt vmcnt(8)
	s_waitcnt lgkmcnt(0)
	s_barrier
	s_setprio 1
	s_waitcnt lgkmcnt(0)
	v_mfma_f32_16x16x32_bf16 v[60:63], v[80:83], v[98:101], v[60:63]
	v_mfma_f32_16x16x32_bf16 v[56:59], v[88:91], v[98:101], v[56:59]
	v_mfma_f32_16x16x32_bf16 v[52:55], v[80:83], v[106:109], v[52:55]
	v_mfma_f32_16x16x32_bf16 v[48:51], v[88:91], v[106:109], v[48:51]
	v_mfma_f32_16x16x32_bf16 v[44:47], v[80:83], v[114:117], v[44:47]
	v_mfma_f32_16x16x32_bf16 v[40:43], v[88:91], v[114:117], v[40:43]
	v_mfma_f32_16x16x32_bf16 v[36:39], v[80:83], v[122:125], v[36:39]
	v_mfma_f32_16x16x32_bf16 v[32:35], v[88:91], v[122:125], v[32:35]
	v_mfma_f32_16x16x32_bf16 v[60:63], v[84:87], v[102:105], v[60:63]
	v_mfma_f32_16x16x32_bf16 v[56:59], v[94:97], v[102:105], v[56:59]
	v_mfma_f32_16x16x32_bf16 v[52:55], v[84:87], v[110:113], v[52:55]
	v_mfma_f32_16x16x32_bf16 v[48:51], v[94:97], v[110:113], v[48:51]
	v_mfma_f32_16x16x32_bf16 v[44:47], v[84:87], v[118:121], v[44:47]
	v_mfma_f32_16x16x32_bf16 v[40:43], v[94:97], v[118:121], v[40:43]
	v_mfma_f32_16x16x32_bf16 v[36:39], v[84:87], v[126:129], v[36:39]
	v_mfma_f32_16x16x32_bf16 v[32:35], v[94:97], v[126:129], v[32:35]
	s_setprio 0
	s_setprio 1
	s_setprio 0
	s_barrier
	s_add_i32 s24, s64, s40
	v_lshl_add_u64 v[130:131], v[130:131], 0, s[80:81]
	s_mov_b32 m0, s24
	global_load_lds_dwordx4 v[130:131], off
	v_lshl_add_u64 v[130:131], v[132:133], 0, s[80:81]
	s_add_i32 m0, s24, 0x2000
	s_nop 0
	global_load_lds_dwordx4 v[130:131], off
	v_lshl_add_u64 v[130:131], v[134:135], 0, s[80:81]
	s_mov_b32 m0, s55
	s_nop 0
	global_load_lds_dwordx4 v[130:131], off
	v_lshl_add_u64 v[130:131], v[136:137], 0, s[80:81]
	s_mov_b32 m0, s56
	s_nop 0
	global_load_lds_dwordx4 v[130:131], off
	v_lshl_add_u64 v[130:131], v[138:139], 0, s[80:81]
	s_mov_b32 m0, s53
	s_nop 0
	global_load_lds_dwordx4 v[130:131], off
	v_lshl_add_u64 v[130:131], v[140:141], 0, s[80:81]
	s_mov_b32 m0, s54
	s_nop 0
	global_load_lds_dwordx4 v[130:131], off
	ds_read_b128 v[98:101], v78 offset:49152
	ds_read_b128 v[102:105], v78 offset:50176
	ds_read_b128 v[106:109], v78 offset:51200
	ds_read_b128 v[110:113], v78 offset:52224
	ds_read_b128 v[114:117], v78 offset:53248
	ds_read_b128 v[118:121], v78 offset:54272
	ds_read_b128 v[122:125], v78 offset:55296
	ds_read_b128 v[126:129], v78 offset:56320
	s_waitcnt vmcnt(8)
	s_waitcnt lgkmcnt(0)
	s_barrier
	s_setprio 1
	s_waitcnt lgkmcnt(0)
	v_mfma_f32_16x16x32_bf16 v[28:31], v[80:83], v[98:101], v[28:31]
	v_mfma_f32_16x16x32_bf16 v[24:27], v[88:91], v[98:101], v[24:27]
	v_mfma_f32_16x16x32_bf16 v[20:23], v[80:83], v[106:109], v[20:23]
	v_mfma_f32_16x16x32_bf16 v[16:19], v[88:91], v[106:109], v[16:19]
	v_mfma_f32_16x16x32_bf16 v[12:15], v[80:83], v[114:117], v[12:15]
	v_mfma_f32_16x16x32_bf16 v[8:11], v[88:91], v[114:117], v[8:11]
	v_mfma_f32_16x16x32_bf16 v[4:7], v[80:83], v[122:125], v[4:7]
	v_mfma_f32_16x16x32_bf16 v[0:3], v[88:91], v[122:125], v[0:3]
	v_mfma_f32_16x16x32_bf16 v[28:31], v[84:87], v[102:105], v[28:31]
	v_mfma_f32_16x16x32_bf16 v[24:27], v[94:97], v[102:105], v[24:27]
	v_mfma_f32_16x16x32_bf16 v[20:23], v[84:87], v[110:113], v[20:23]
	v_mfma_f32_16x16x32_bf16 v[16:19], v[94:97], v[110:113], v[16:19]
	v_mfma_f32_16x16x32_bf16 v[12:15], v[84:87], v[118:121], v[12:15]
	v_mfma_f32_16x16x32_bf16 v[8:11], v[94:97], v[118:121], v[8:11]
	v_mfma_f32_16x16x32_bf16 v[4:7], v[84:87], v[126:129], v[4:7]
	v_mfma_f32_16x16x32_bf16 v[0:3], v[94:97], v[126:129], v[0:3]
	s_setprio 0
	s_setprio 1
	s_setprio 0
	s_barrier
	s_add_u32 s26, s26, 0x100
	s_addc_u32 s27, s27, 0
	s_add_u32 s61, s61, 0x100
	s_addc_u32 s62, s62, 0
	s_cmp_ge_i32 s63, s51
	s_mov_b32 s24, s63
	s_cbranch_scc0 .LBB0_962

.LBB0_1518:
	s_add_i32 s63, s30, 2
	s_add_u32 s64, s28, 0x80
	s_addc_u32 s31, s29, 0
	s_add_i32 s66, 0, 0x10000
	s_cmp_eq_u32 s55, s30
	s_cselect_b32 s31, s7, s31
	s_cselect_b32 s30, s6, s64
	s_cselect_b32 s65, s27, s62
	s_cselect_b32 s64, s26, s61
	s_add_i32 s67, 0, 0x14000
	v_add_u32_e32 v142, s66, v164
	v_add_u32_e32 v156, s67, v164
	ds_read_b128 v[130:133], v142
	ds_read_b128 v[134:137], v142 offset:1024
	ds_read_b128 v[138:141], v142 offset:2048
	ds_read_b128 v[142:145], v142 offset:3072
	ds_read_b128 v[160:163], v156
	ds_read_b128 v[168:171], v156 offset:1024
	ds_read_b128 v[172:175], v156 offset:2048
	ds_read_b128 v[176:179], v156 offset:3072
	v_lshl_add_u64 v[156:157], s[28:29], 0, v[152:153]
	s_add_i32 m0, s46, 0xc000
	ds_read_b128 v[180:183], v166
	ds_read_b128 v[184:187], v166 offset:1024
	ds_read_b128 v[188:191], v166 offset:2048
	ds_read_b128 v[192:195], v166 offset:3072
	ds_read_b128 v[214:217], v166 offset:4096
	ds_read_b128 v[218:221], v166 offset:5120
	ds_read_b128 v[222:225], v166 offset:6144
	ds_read_b128 v[226:229], v166 offset:7168
	global_load_lds_dwordx4 v[156:157], off
	v_lshl_add_u64 v[156:157], s[28:29], 0, v[154:155]
	s_add_i32 m0, s46, 0xe000
	s_nop 0
	global_load_lds_dwordx4 v[156:157], off
	s_waitcnt vmcnt(8)
	s_waitcnt lgkmcnt(0)
	s_barrier
	s_setprio 1
	s_waitcnt lgkmcnt(0)
	v_mfma_f32_16x16x32_bf16 v[126:129], v[130:133], v[180:183], v[126:129]
	v_mfma_f32_16x16x32_bf16 v[122:125], v[138:141], v[180:183], v[122:125]
	v_mfma_f32_16x16x32_bf16 v[110:113], v[130:133], v[188:191], v[110:113]
	v_mfma_f32_16x16x32_bf16 v[106:109], v[138:141], v[188:191], v[106:109]
	v_mfma_f32_16x16x32_bf16 v[94:97], v[130:133], v[214:217], v[94:97]
	v_mfma_f32_16x16x32_bf16 v[88:91], v[138:141], v[214:217], v[88:91]
	v_mfma_f32_16x16x32_bf16 v[76:79], v[130:133], v[222:225], v[76:79]
	v_mfma_f32_16x16x32_bf16 v[72:75], v[138:141], v[222:225], v[72:75]
	v_mfma_f32_16x16x32_bf16 v[126:129], v[134:137], v[184:187], v[126:129]
	v_mfma_f32_16x16x32_bf16 v[122:125], v[142:145], v[184:187], v[122:125]
	v_mfma_f32_16x16x32_bf16 v[110:113], v[134:137], v[192:195], v[110:113]
	v_mfma_f32_16x16x32_bf16 v[106:109], v[142:145], v[192:195], v[106:109]
	v_mfma_f32_16x16x32_bf16 v[94:97], v[134:137], v[218:221], v[94:97]
	v_mfma_f32_16x16x32_bf16 v[88:91], v[142:145], v[218:221], v[88:91]
	v_mfma_f32_16x16x32_bf16 v[76:79], v[134:137], v[226:229], v[76:79]
	v_mfma_f32_16x16x32_bf16 v[72:75], v[142:145], v[226:229], v[72:75]
	s_setprio 0
	s_setprio 1
	v_mfma_f32_16x16x32_bf16 v[118:121], v[160:163], v[180:183], v[118:121]
	v_mfma_f32_16x16x32_bf16 v[114:117], v[172:175], v[180:183], v[114:117]
	v_mfma_f32_16x16x32_bf16 v[102:105], v[160:163], v[188:191], v[102:105]
	v_mfma_f32_16x16x32_bf16 v[98:101], v[172:175], v[188:191], v[98:101]
	v_mfma_f32_16x16x32_bf16 v[84:87], v[160:163], v[214:217], v[84:87]
	v_mfma_f32_16x16x32_bf16 v[80:83], v[172:175], v[214:217], v[80:83]
	v_mfma_f32_16x16x32_bf16 v[68:71], v[160:163], v[222:225], v[68:71]
	v_mfma_f32_16x16x32_bf16 v[64:67], v[172:175], v[222:225], v[64:67]
	v_mfma_f32_16x16x32_bf16 v[118:121], v[168:171], v[184:187], v[118:121]
	v_mfma_f32_16x16x32_bf16 v[114:117], v[176:179], v[184:187], v[114:117]
	v_mfma_f32_16x16x32_bf16 v[102:105], v[168:171], v[192:195], v[102:105]
	v_mfma_f32_16x16x32_bf16 v[98:101], v[176:179], v[192:195], v[98:101]
	v_mfma_f32_16x16x32_bf16 v[84:87], v[168:171], v[218:221], v[84:87]
	v_mfma_f32_16x16x32_bf16 v[80:83], v[176:179], v[218:221], v[80:83]
	v_mfma_f32_16x16x32_bf16 v[68:71], v[168:171], v[226:229], v[68:71]
	v_mfma_f32_16x16x32_bf16 v[64:67], v[176:179], v[226:229], v[64:67]
	s_setprio 0
	s_barrier
	s_add_i32 s66, s66, s41
	v_lshl_add_u64 v[156:157], s[64:65], 0, v[92:93]
	s_mov_b32 m0, s66
	global_load_lds_dwordx4 v[156:157], off
	s_add_i32 m0, s66, 0x2000
	v_lshl_add_u64 v[230:231], s[64:65], 0, v[150:151]
	s_add_u32 s64, s64, s8
	s_addc_u32 s65, s65, s9
	s_add_i32 s66, s67, s41
	global_load_lds_dwordx4 v[230:231], off
	v_lshl_add_u64 v[232:233], s[64:65], 0, v[92:93]
	s_mov_b32 m0, s66
	v_lshl_add_u64 v[234:235], s[64:65], 0, v[150:151]
	global_load_lds_dwordx4 v[232:233], off
	s_add_i32 m0, s66, 0x2000
	v_lshl_add_u64 v[236:237], s[30:31], 0, v[146:147]
	global_load_lds_dwordx4 v[234:235], off
	s_mov_b32 m0, s46
	v_lshl_add_u64 v[238:239], s[30:31], 0, v[148:149]
	global_load_lds_dwordx4 v[236:237], off
	s_mov_b32 m0, s47
	s_nop 0
	global_load_lds_dwordx4 v[238:239], off
	ds_read_b128 v[180:183], v166 offset:16384
	ds_read_b128 v[184:187], v166 offset:17408
	ds_read_b128 v[188:191], v166 offset:18432
	ds_read_b128 v[192:195], v166 offset:19456
	ds_read_b128 v[214:217], v166 offset:20480
	ds_read_b128 v[218:221], v166 offset:21504
	ds_read_b128 v[222:225], v166 offset:22528
	ds_read_b128 v[226:229], v166 offset:23552
	s_waitcnt vmcnt(8)
	s_waitcnt lgkmcnt(0)
	s_barrier
	s_setprio 1
	s_waitcnt lgkmcnt(0)
	v_mfma_f32_16x16x32_bf16 v[60:63], v[130:133], v[180:183], v[60:63]
	v_mfma_f32_16x16x32_bf16 v[56:59], v[138:141], v[180:183], v[56:59]
	v_mfma_f32_16x16x32_bf16 v[44:47], v[130:133], v[188:191], v[44:47]
	v_mfma_f32_16x16x32_bf16 v[40:43], v[138:141], v[188:191], v[40:43]
	v_mfma_f32_16x16x32_bf16 v[28:31], v[130:133], v[214:217], v[28:31]
	v_mfma_f32_16x16x32_bf16 v[24:27], v[138:141], v[214:217], v[24:27]
	v_mfma_f32_16x16x32_bf16 v[12:15], v[130:133], v[222:225], v[12:15]
	v_mfma_f32_16x16x32_bf16 v[8:11], v[138:141], v[222:225], v[8:11]
	v_mfma_f32_16x16x32_bf16 v[60:63], v[134:137], v[184:187], v[60:63]
	v_mfma_f32_16x16x32_bf16 v[56:59], v[142:145], v[184:187], v[56:59]
	v_mfma_f32_16x16x32_bf16 v[44:47], v[134:137], v[192:195], v[44:47]
	v_mfma_f32_16x16x32_bf16 v[40:43], v[142:145], v[192:195], v[40:43]
	v_mfma_f32_16x16x32_bf16 v[28:31], v[134:137], v[218:221], v[28:31]
	v_mfma_f32_16x16x32_bf16 v[24:27], v[142:145], v[218:221], v[24:27]
	v_mfma_f32_16x16x32_bf16 v[12:15], v[134:137], v[226:229], v[12:15]
	v_mfma_f32_16x16x32_bf16 v[8:11], v[142:145], v[226:229], v[8:11]
	s_setprio 0
	s_setprio 1
	v_mfma_f32_16x16x32_bf16 v[52:55], v[160:163], v[180:183], v[52:55]
	v_mfma_f32_16x16x32_bf16 v[48:51], v[172:175], v[180:183], v[48:51]
	v_mfma_f32_16x16x32_bf16 v[36:39], v[160:163], v[188:191], v[36:39]
	v_mfma_f32_16x16x32_bf16 v[32:35], v[172:175], v[188:191], v[32:35]
	v_mfma_f32_16x16x32_bf16 v[20:23], v[160:163], v[214:217], v[20:23]
	v_mfma_f32_16x16x32_bf16 v[16:19], v[172:175], v[214:217], v[16:19]
	v_mfma_f32_16x16x32_bf16 v[4:7], v[160:163], v[222:225], v[4:7]
	v_mfma_f32_16x16x32_bf16 v[0:3], v[172:175], v[222:225], v[0:3]
	v_mfma_f32_16x16x32_bf16 v[52:55], v[168:171], v[184:187], v[52:55]
	v_mfma_f32_16x16x32_bf16 v[48:51], v[176:179], v[184:187], v[48:51]
	v_mfma_f32_16x16x32_bf16 v[36:39], v[168:171], v[192:195], v[36:39]
	v_mfma_f32_16x16x32_bf16 v[32:35], v[176:179], v[192:195], v[32:35]
	v_mfma_f32_16x16x32_bf16 v[20:23], v[168:171], v[218:221], v[20:23]
	v_mfma_f32_16x16x32_bf16 v[16:19], v[176:179], v[218:221], v[16:19]
	v_mfma_f32_16x16x32_bf16 v[4:7], v[168:171], v[226:229], v[4:7]
	v_mfma_f32_16x16x32_bf16 v[0:3], v[176:179], v[226:229], v[0:3]
	s_setprio 0
	s_barrier
	s_add_i32 s64, 0, 0x18000
	s_add_i32 s65, 0, 0x1c000
	v_add_u32_e32 v142, s64, v164
	v_add_u32_e32 v167, s65, v164
	ds_read_b128 v[130:133], v142
	ds_read_b128 v[134:137], v142 offset:1024
	ds_read_b128 v[138:141], v142 offset:2048
	ds_read_b128 v[142:145], v142 offset:3072
	ds_read_b128 v[160:163], v167
	ds_read_b128 v[168:171], v167 offset:1024
	ds_read_b128 v[172:175], v167 offset:2048
	ds_read_b128 v[176:179], v167 offset:3072
	s_add_u32 s30, s30, s12
	s_addc_u32 s31, s31, s13
	s_mov_b32 m0, s48
	v_lshl_add_u64 v[240:241], s[30:31], 0, v[146:147]
	ds_read_b128 v[180:183], v166 offset:32768
	ds_read_b128 v[184:187], v166 offset:33792
	ds_read_b128 v[188:191], v166 offset:34816
	ds_read_b128 v[192:195], v166 offset:35840
	ds_read_b128 v[214:217], v166 offset:36864
	ds_read_b128 v[218:221], v166 offset:37888
	ds_read_b128 v[222:225], v166 offset:38912
	ds_read_b128 v[226:229], v166 offset:39936
	global_load_lds_dwordx4 v[240:241], off
	v_lshl_add_u64 v[240:241], s[30:31], 0, v[148:149]
	s_mov_b32 m0, s49
	s_nop 0
	global_load_lds_dwordx4 v[240:241], off
	s_waitcnt vmcnt(8)
	s_waitcnt lgkmcnt(0)
	s_barrier
	s_setprio 1
	s_waitcnt lgkmcnt(0)
	v_mfma_f32_16x16x32_bf16 v[126:129], v[130:133], v[180:183], v[126:129]
	v_mfma_f32_16x16x32_bf16 v[122:125], v[138:141], v[180:183], v[122:125]
	v_mfma_f32_16x16x32_bf16 v[110:113], v[130:133], v[188:191], v[110:113]
	v_mfma_f32_16x16x32_bf16 v[106:109], v[138:141], v[188:191], v[106:109]
	v_mfma_f32_16x16x32_bf16 v[94:97], v[130:133], v[214:217], v[94:97]
	v_mfma_f32_16x16x32_bf16 v[88:91], v[138:141], v[214:217], v[88:91]
	v_mfma_f32_16x16x32_bf16 v[76:79], v[130:133], v[222:225], v[76:79]
	v_mfma_f32_16x16x32_bf16 v[72:75], v[138:141], v[222:225], v[72:75]
	v_mfma_f32_16x16x32_bf16 v[126:129], v[134:137], v[184:187], v[126:129]
	v_mfma_f32_16x16x32_bf16 v[122:125], v[142:145], v[184:187], v[122:125]
	v_mfma_f32_16x16x32_bf16 v[110:113], v[134:137], v[192:195], v[110:113]
	v_mfma_f32_16x16x32_bf16 v[106:109], v[142:145], v[192:195], v[106:109]
	v_mfma_f32_16x16x32_bf16 v[94:97], v[134:137], v[218:221], v[94:97]
	v_mfma_f32_16x16x32_bf16 v[88:91], v[142:145], v[218:221], v[88:91]
	v_mfma_f32_16x16x32_bf16 v[76:79], v[134:137], v[226:229], v[76:79]
	v_mfma_f32_16x16x32_bf16 v[72:75], v[142:145], v[226:229], v[72:75]
	s_setprio 0
	s_setprio 1
	v_mfma_f32_16x16x32_bf16 v[118:121], v[160:163], v[180:183], v[118:121]
	v_mfma_f32_16x16x32_bf16 v[114:117], v[172:175], v[180:183], v[114:117]
	v_mfma_f32_16x16x32_bf16 v[102:105], v[160:163], v[188:191], v[102:105]
	v_mfma_f32_16x16x32_bf16 v[98:101], v[172:175], v[188:191], v[98:101]
	v_mfma_f32_16x16x32_bf16 v[84:87], v[160:163], v[214:217], v[84:87]
	v_mfma_f32_16x16x32_bf16 v[80:83], v[172:175], v[214:217], v[80:83]
	v_mfma_f32_16x16x32_bf16 v[68:71], v[160:163], v[222:225], v[68:71]
	v_mfma_f32_16x16x32_bf16 v[64:67], v[172:175], v[222:225], v[64:67]
	v_mfma_f32_16x16x32_bf16 v[118:121], v[168:171], v[184:187], v[118:121]
	v_mfma_f32_16x16x32_bf16 v[114:117], v[176:179], v[184:187], v[114:117]
	v_mfma_f32_16x16x32_bf16 v[102:105], v[168:171], v[192:195], v[102:105]
	v_mfma_f32_16x16x32_bf16 v[98:101], v[176:179], v[192:195], v[98:101]
	v_mfma_f32_16x16x32_bf16 v[84:87], v[168:171], v[218:221], v[84:87]
	v_mfma_f32_16x16x32_bf16 v[80:83], v[176:179], v[218:221], v[80:83]
	v_mfma_f32_16x16x32_bf16 v[68:71], v[168:171], v[226:229], v[68:71]
	v_mfma_f32_16x16x32_bf16 v[64:67], v[176:179], v[226:229], v[64:67]
	s_setprio 0
	s_barrier
	s_add_i32 s30, s64, s41
	v_lshl_add_u64 v[156:157], v[156:157], 0, s[80:81]
	s_mov_b32 m0, s30
	global_load_lds_dwordx4 v[156:157], off
	v_lshl_add_u64 v[156:157], v[230:231], 0, s[80:81]
	s_add_i32 m0, s30, 0x2000
	s_add_i32 s30, s65, s41
	global_load_lds_dwordx4 v[156:157], off
	v_lshl_add_u64 v[156:157], v[232:233], 0, s[80:81]
	s_mov_b32 m0, s30
	s_nop 0
	global_load_lds_dwordx4 v[156:157], off
	v_lshl_add_u64 v[156:157], v[234:235], 0, s[80:81]
	s_add_i32 m0, s30, 0x2000
	s_nop 0
	global_load_lds_dwordx4 v[156:157], off
	v_lshl_add_u64 v[156:157], v[236:237], 0, s[80:81]
	s_mov_b32 m0, s53
	s_nop 0
	global_load_lds_dwordx4 v[156:157], off
	v_lshl_add_u64 v[156:157], v[238:239], 0, s[80:81]
	s_mov_b32 m0, s54
	s_nop 0
	global_load_lds_dwordx4 v[156:157], off
	ds_read_b128 v[180:183], v166 offset:49152
	ds_read_b128 v[184:187], v166 offset:50176
	ds_read_b128 v[188:191], v166 offset:51200
	ds_read_b128 v[192:195], v166 offset:52224
	ds_read_b128 v[214:217], v166 offset:53248
	ds_read_b128 v[218:221], v166 offset:54272
	ds_read_b128 v[222:225], v166 offset:55296
	ds_read_b128 v[226:229], v166 offset:56320
	s_waitcnt vmcnt(8)
	s_waitcnt lgkmcnt(0)
	s_barrier
	s_setprio 1
	s_waitcnt lgkmcnt(0)
	v_mfma_f32_16x16x32_bf16 v[60:63], v[130:133], v[180:183], v[60:63]
	v_mfma_f32_16x16x32_bf16 v[56:59], v[138:141], v[180:183], v[56:59]
	v_mfma_f32_16x16x32_bf16 v[44:47], v[130:133], v[188:191], v[44:47]
	v_mfma_f32_16x16x32_bf16 v[40:43], v[138:141], v[188:191], v[40:43]
	v_mfma_f32_16x16x32_bf16 v[28:31], v[130:133], v[214:217], v[28:31]
	v_mfma_f32_16x16x32_bf16 v[24:27], v[138:141], v[214:217], v[24:27]
	v_mfma_f32_16x16x32_bf16 v[12:15], v[130:133], v[222:225], v[12:15]
	v_mfma_f32_16x16x32_bf16 v[8:11], v[138:141], v[222:225], v[8:11]
	v_mfma_f32_16x16x32_bf16 v[60:63], v[134:137], v[184:187], v[60:63]
	v_mfma_f32_16x16x32_bf16 v[56:59], v[142:145], v[184:187], v[56:59]
	v_mfma_f32_16x16x32_bf16 v[44:47], v[134:137], v[192:195], v[44:47]
	v_mfma_f32_16x16x32_bf16 v[40:43], v[142:145], v[192:195], v[40:43]
	v_mfma_f32_16x16x32_bf16 v[28:31], v[134:137], v[218:221], v[28:31]
	v_mfma_f32_16x16x32_bf16 v[24:27], v[142:145], v[218:221], v[24:27]
	v_mfma_f32_16x16x32_bf16 v[12:15], v[134:137], v[226:229], v[12:15]
	v_mfma_f32_16x16x32_bf16 v[8:11], v[142:145], v[226:229], v[8:11]
	s_setprio 0
	s_setprio 1
	v_mfma_f32_16x16x32_bf16 v[52:55], v[160:163], v[180:183], v[52:55]
	v_mfma_f32_16x16x32_bf16 v[48:51], v[172:175], v[180:183], v[48:51]
	v_mfma_f32_16x16x32_bf16 v[36:39], v[160:163], v[188:191], v[36:39]
	v_mfma_f32_16x16x32_bf16 v[32:35], v[172:175], v[188:191], v[32:35]
	v_mfma_f32_16x16x32_bf16 v[20:23], v[160:163], v[214:217], v[20:23]
	v_mfma_f32_16x16x32_bf16 v[16:19], v[172:175], v[214:217], v[16:19]
	v_mfma_f32_16x16x32_bf16 v[4:7], v[160:163], v[222:225], v[4:7]
	v_mfma_f32_16x16x32_bf16 v[0:3], v[172:175], v[222:225], v[0:3]
	v_mfma_f32_16x16x32_bf16 v[52:55], v[168:171], v[184:187], v[52:55]
	v_mfma_f32_16x16x32_bf16 v[48:51], v[176:179], v[184:187], v[48:51]
	v_mfma_f32_16x16x32_bf16 v[36:39], v[168:171], v[192:195], v[36:39]
	v_mfma_f32_16x16x32_bf16 v[32:35], v[176:179], v[192:195], v[32:35]
	v_mfma_f32_16x16x32_bf16 v[20:23], v[168:171], v[218:221], v[20:23]
	v_mfma_f32_16x16x32_bf16 v[16:19], v[176:179], v[218:221], v[16:19]
	v_mfma_f32_16x16x32_bf16 v[4:7], v[168:171], v[226:229], v[4:7]
	v_mfma_f32_16x16x32_bf16 v[0:3], v[176:179], v[226:229], v[0:3]
	s_setprio 0
	s_barrier
	s_add_u32 s28, s28, 0x100
	s_addc_u32 s29, s29, 0
	s_add_u32 s61, s61, 0x100
	s_addc_u32 s62, s62, 0
	s_cmp_ge_i32 s63, s52
	s_mov_b32 s30, s63
	s_cbranch_scc0 .LBB0_1518
	s_movk_i32 s67, 0x4000

.LBB0_1603:
	s_add_i32 s59, s28, 2
	s_add_u32 s60, s26, 0x80
	s_addc_u32 s29, s27, 0
	s_add_i32 s62, 0, 0x10000
	s_cmp_eq_u32 s53, s28
	s_cselect_b32 s29, s7, s29
	s_cselect_b32 s28, s6, s60
	v_add_u32_e32 v156, s62, v141
	s_cselect_b32 s61, s25, s58
	s_cselect_b32 s60, s24, s57
	s_add_i32 s63, 0, 0x14000
	ds_read_b128 v[144:147], v156
	ds_read_b128 v[148:151], v156 offset:1024
	ds_read_b128 v[152:155], v156 offset:2048
	ds_read_b128 v[160:163], v156 offset:3072
	v_add_u32_e32 v156, s63, v141
	ds_read_b128 v[164:167], v156
	ds_read_b128 v[168:171], v156 offset:1024
	ds_read_b128 v[172:175], v156 offset:2048
	ds_read_b128 v[176:179], v156 offset:3072
	v_lshl_add_u64 v[156:157], s[26:27], 0, v[136:137]
	s_add_i32 m0, s44, 0xc000
	ds_read_b128 v[180:183], v143
	ds_read_b128 v[184:187], v143 offset:1024
	ds_read_b128 v[188:191], v143 offset:2048
	ds_read_b128 v[192:195], v143 offset:3072
	ds_read_b128 v[214:217], v143 offset:4096
	ds_read_b128 v[218:221], v143 offset:5120
	ds_read_b128 v[222:225], v143 offset:6144
	ds_read_b128 v[226:229], v143 offset:7168
	global_load_lds_dwordx4 v[156:157], off
	v_lshl_add_u64 v[156:157], s[26:27], 0, v[138:139]
	s_add_i32 m0, s44, 0xe000
	s_nop 0
	global_load_lds_dwordx4 v[156:157], off
	s_waitcnt vmcnt(8)
	s_waitcnt lgkmcnt(0)
	s_barrier
	s_setprio 1
	s_waitcnt lgkmcnt(0)
	v_mfma_f32_16x16x32_bf16 v[122:125], v[144:147], v[180:183], v[122:125]
	v_mfma_f32_16x16x32_bf16 v[126:129], v[152:155], v[180:183], v[126:129]
	v_mfma_f32_16x16x32_bf16 v[110:113], v[144:147], v[188:191], v[110:113]
	v_mfma_f32_16x16x32_bf16 v[106:109], v[152:155], v[188:191], v[106:109]
	v_mfma_f32_16x16x32_bf16 v[94:97], v[144:147], v[214:217], v[94:97]
	v_mfma_f32_16x16x32_bf16 v[88:91], v[152:155], v[214:217], v[88:91]
	v_mfma_f32_16x16x32_bf16 v[76:79], v[144:147], v[222:225], v[76:79]
	v_mfma_f32_16x16x32_bf16 v[72:75], v[152:155], v[222:225], v[72:75]
	v_mfma_f32_16x16x32_bf16 v[122:125], v[148:151], v[184:187], v[122:125]
	v_mfma_f32_16x16x32_bf16 v[126:129], v[160:163], v[184:187], v[126:129]
	v_mfma_f32_16x16x32_bf16 v[110:113], v[148:151], v[192:195], v[110:113]
	v_mfma_f32_16x16x32_bf16 v[106:109], v[160:163], v[192:195], v[106:109]
	v_mfma_f32_16x16x32_bf16 v[94:97], v[148:151], v[218:221], v[94:97]
	v_mfma_f32_16x16x32_bf16 v[88:91], v[160:163], v[218:221], v[88:91]
	v_mfma_f32_16x16x32_bf16 v[76:79], v[148:151], v[226:229], v[76:79]
	v_mfma_f32_16x16x32_bf16 v[72:75], v[160:163], v[226:229], v[72:75]
	s_setprio 0
	s_setprio 1
	v_mfma_f32_16x16x32_bf16 v[118:121], v[164:167], v[180:183], v[118:121]
	v_mfma_f32_16x16x32_bf16 v[114:117], v[172:175], v[180:183], v[114:117]
	v_mfma_f32_16x16x32_bf16 v[102:105], v[164:167], v[188:191], v[102:105]
	v_mfma_f32_16x16x32_bf16 v[98:101], v[172:175], v[188:191], v[98:101]
	v_mfma_f32_16x16x32_bf16 v[84:87], v[164:167], v[214:217], v[84:87]
	v_mfma_f32_16x16x32_bf16 v[80:83], v[172:175], v[214:217], v[80:83]
	v_mfma_f32_16x16x32_bf16 v[68:71], v[164:167], v[222:225], v[68:71]
	v_mfma_f32_16x16x32_bf16 v[64:67], v[172:175], v[222:225], v[64:67]
	v_mfma_f32_16x16x32_bf16 v[118:121], v[168:171], v[184:187], v[118:121]
	v_mfma_f32_16x16x32_bf16 v[114:117], v[176:179], v[184:187], v[114:117]
	v_mfma_f32_16x16x32_bf16 v[102:105], v[168:171], v[192:195], v[102:105]
	v_mfma_f32_16x16x32_bf16 v[98:101], v[176:179], v[192:195], v[98:101]
	v_mfma_f32_16x16x32_bf16 v[84:87], v[168:171], v[218:221], v[84:87]
	v_mfma_f32_16x16x32_bf16 v[80:83], v[176:179], v[218:221], v[80:83]
	v_mfma_f32_16x16x32_bf16 v[68:71], v[168:171], v[226:229], v[68:71]
	v_mfma_f32_16x16x32_bf16 v[64:67], v[176:179], v[226:229], v[64:67]
	s_setprio 0
	s_barrier
	s_add_i32 s62, s62, s39
	v_lshl_add_u64 v[156:157], s[60:61], 0, v[92:93]
	s_mov_b32 m0, s62
	global_load_lds_dwordx4 v[156:157], off
	s_add_i32 m0, s62, 0x2000
	v_lshl_add_u64 v[230:231], s[60:61], 0, v[134:135]
	s_add_u32 s60, s60, s8
	s_addc_u32 s61, s61, s9
	s_add_i32 s62, s63, s39
	global_load_lds_dwordx4 v[230:231], off
	v_lshl_add_u64 v[232:233], s[60:61], 0, v[92:93]
	s_mov_b32 m0, s62
	v_lshl_add_u64 v[234:235], s[60:61], 0, v[134:135]
	global_load_lds_dwordx4 v[232:233], off
	s_add_i32 m0, s62, 0x2000
	v_lshl_add_u64 v[236:237], s[28:29], 0, v[130:131]
	global_load_lds_dwordx4 v[234:235], off
	s_mov_b32 m0, s44
	v_lshl_add_u64 v[238:239], s[28:29], 0, v[132:133]
	global_load_lds_dwordx4 v[236:237], off
	s_mov_b32 m0, s45
	s_nop 0
	global_load_lds_dwordx4 v[238:239], off
	ds_read_b128 v[180:183], v143 offset:16384
	ds_read_b128 v[184:187], v143 offset:17408
	ds_read_b128 v[188:191], v143 offset:18432
	ds_read_b128 v[192:195], v143 offset:19456
	ds_read_b128 v[214:217], v143 offset:20480
	ds_read_b128 v[218:221], v143 offset:21504
	ds_read_b128 v[222:225], v143 offset:22528
	ds_read_b128 v[226:229], v143 offset:23552
	s_waitcnt vmcnt(8)
	s_waitcnt lgkmcnt(0)
	s_barrier
	s_setprio 1
	s_waitcnt lgkmcnt(0)
	v_mfma_f32_16x16x32_bf16 v[60:63], v[144:147], v[180:183], v[60:63]
	v_mfma_f32_16x16x32_bf16 v[56:59], v[152:155], v[180:183], v[56:59]
	v_mfma_f32_16x16x32_bf16 v[44:47], v[144:147], v[188:191], v[44:47]
	v_mfma_f32_16x16x32_bf16 v[40:43], v[152:155], v[188:191], v[40:43]
	v_mfma_f32_16x16x32_bf16 v[28:31], v[144:147], v[214:217], v[28:31]
	v_mfma_f32_16x16x32_bf16 v[24:27], v[152:155], v[214:217], v[24:27]
	v_mfma_f32_16x16x32_bf16 v[12:15], v[144:147], v[222:225], v[12:15]
	v_mfma_f32_16x16x32_bf16 v[8:11], v[152:155], v[222:225], v[8:11]
	v_mfma_f32_16x16x32_bf16 v[60:63], v[148:151], v[184:187], v[60:63]
	v_mfma_f32_16x16x32_bf16 v[56:59], v[160:163], v[184:187], v[56:59]
	v_mfma_f32_16x16x32_bf16 v[44:47], v[148:151], v[192:195], v[44:47]
	v_mfma_f32_16x16x32_bf16 v[40:43], v[160:163], v[192:195], v[40:43]
	v_mfma_f32_16x16x32_bf16 v[28:31], v[148:151], v[218:221], v[28:31]
	v_mfma_f32_16x16x32_bf16 v[24:27], v[160:163], v[218:221], v[24:27]
	v_mfma_f32_16x16x32_bf16 v[12:15], v[148:151], v[226:229], v[12:15]
	v_mfma_f32_16x16x32_bf16 v[8:11], v[160:163], v[226:229], v[8:11]
	s_setprio 0
	s_setprio 1
	v_mfma_f32_16x16x32_bf16 v[52:55], v[164:167], v[180:183], v[52:55]
	v_mfma_f32_16x16x32_bf16 v[48:51], v[172:175], v[180:183], v[48:51]
	v_mfma_f32_16x16x32_bf16 v[36:39], v[164:167], v[188:191], v[36:39]
	v_mfma_f32_16x16x32_bf16 v[32:35], v[172:175], v[188:191], v[32:35]
	v_mfma_f32_16x16x32_bf16 v[20:23], v[164:167], v[214:217], v[20:23]
	v_mfma_f32_16x16x32_bf16 v[16:19], v[172:175], v[214:217], v[16:19]
	v_mfma_f32_16x16x32_bf16 v[4:7], v[164:167], v[222:225], v[4:7]
	v_mfma_f32_16x16x32_bf16 v[0:3], v[172:175], v[222:225], v[0:3]
	v_mfma_f32_16x16x32_bf16 v[52:55], v[168:171], v[184:187], v[52:55]
	v_mfma_f32_16x16x32_bf16 v[48:51], v[176:179], v[184:187], v[48:51]
	v_mfma_f32_16x16x32_bf16 v[36:39], v[168:171], v[192:195], v[36:39]
	v_mfma_f32_16x16x32_bf16 v[32:35], v[176:179], v[192:195], v[32:35]
	v_mfma_f32_16x16x32_bf16 v[20:23], v[168:171], v[218:221], v[20:23]
	v_mfma_f32_16x16x32_bf16 v[16:19], v[176:179], v[218:221], v[16:19]
	v_mfma_f32_16x16x32_bf16 v[4:7], v[168:171], v[226:229], v[4:7]
	v_mfma_f32_16x16x32_bf16 v[0:3], v[176:179], v[226:229], v[0:3]
	s_setprio 0
	s_barrier
	s_add_i32 s60, 0, 0x18000
	v_add_u32_e32 v159, s60, v141
	s_add_i32 s61, 0, 0x1c000
	ds_read_b128 v[144:147], v159
	ds_read_b128 v[148:151], v159 offset:1024
	ds_read_b128 v[152:155], v159 offset:2048
	ds_read_b128 v[160:163], v159 offset:3072
	v_add_u32_e32 v159, s61, v141
	ds_read_b128 v[164:167], v159
	ds_read_b128 v[168:171], v159 offset:1024
	ds_read_b128 v[172:175], v159 offset:2048
	ds_read_b128 v[176:179], v159 offset:3072
	s_add_u32 s28, s28, s12
	s_addc_u32 s29, s29, s13
	s_mov_b32 m0, s46
	v_lshl_add_u64 v[240:241], s[28:29], 0, v[130:131]
	ds_read_b128 v[180:183], v143 offset:32768
	ds_read_b128 v[184:187], v143 offset:33792
	ds_read_b128 v[188:191], v143 offset:34816
	ds_read_b128 v[192:195], v143 offset:35840
	ds_read_b128 v[214:217], v143 offset:36864
	ds_read_b128 v[218:221], v143 offset:37888
	ds_read_b128 v[222:225], v143 offset:38912
	ds_read_b128 v[226:229], v143 offset:39936
	global_load_lds_dwordx4 v[240:241], off
	v_lshl_add_u64 v[240:241], s[28:29], 0, v[132:133]
	s_mov_b32 m0, s47
	s_nop 0
	global_load_lds_dwordx4 v[240:241], off
	s_waitcnt vmcnt(8)
	s_waitcnt lgkmcnt(0)
	s_barrier
	s_setprio 1
	s_waitcnt lgkmcnt(0)
	v_mfma_f32_16x16x32_bf16 v[122:125], v[144:147], v[180:183], v[122:125]
	v_mfma_f32_16x16x32_bf16 v[126:129], v[152:155], v[180:183], v[126:129]
	v_mfma_f32_16x16x32_bf16 v[110:113], v[144:147], v[188:191], v[110:113]
	v_mfma_f32_16x16x32_bf16 v[106:109], v[152:155], v[188:191], v[106:109]
	v_mfma_f32_16x16x32_bf16 v[94:97], v[144:147], v[214:217], v[94:97]
	v_mfma_f32_16x16x32_bf16 v[88:91], v[152:155], v[214:217], v[88:91]
	v_mfma_f32_16x16x32_bf16 v[76:79], v[144:147], v[222:225], v[76:79]
	v_mfma_f32_16x16x32_bf16 v[72:75], v[152:155], v[222:225], v[72:75]
	v_mfma_f32_16x16x32_bf16 v[122:125], v[148:151], v[184:187], v[122:125]
	v_mfma_f32_16x16x32_bf16 v[126:129], v[160:163], v[184:187], v[126:129]
	v_mfma_f32_16x16x32_bf16 v[110:113], v[148:151], v[192:195], v[110:113]
	v_mfma_f32_16x16x32_bf16 v[106:109], v[160:163], v[192:195], v[106:109]
	v_mfma_f32_16x16x32_bf16 v[94:97], v[148:151], v[218:221], v[94:97]
	v_mfma_f32_16x16x32_bf16 v[88:91], v[160:163], v[218:221], v[88:91]
	v_mfma_f32_16x16x32_bf16 v[76:79], v[148:151], v[226:229], v[76:79]
	v_mfma_f32_16x16x32_bf16 v[72:75], v[160:163], v[226:229], v[72:75]
	s_setprio 0
	s_setprio 1
	v_mfma_f32_16x16x32_bf16 v[118:121], v[164:167], v[180:183], v[118:121]
	v_mfma_f32_16x16x32_bf16 v[114:117], v[172:175], v[180:183], v[114:117]
	v_mfma_f32_16x16x32_bf16 v[102:105], v[164:167], v[188:191], v[102:105]
	v_mfma_f32_16x16x32_bf16 v[98:101], v[172:175], v[188:191], v[98:101]
	v_mfma_f32_16x16x32_bf16 v[84:87], v[164:167], v[214:217], v[84:87]
	v_mfma_f32_16x16x32_bf16 v[80:83], v[172:175], v[214:217], v[80:83]
	v_mfma_f32_16x16x32_bf16 v[68:71], v[164:167], v[222:225], v[68:71]
	v_mfma_f32_16x16x32_bf16 v[64:67], v[172:175], v[222:225], v[64:67]
	v_mfma_f32_16x16x32_bf16 v[118:121], v[168:171], v[184:187], v[118:121]
	v_mfma_f32_16x16x32_bf16 v[114:117], v[176:179], v[184:187], v[114:117]
	v_mfma_f32_16x16x32_bf16 v[102:105], v[168:171], v[192:195], v[102:105]
	v_mfma_f32_16x16x32_bf16 v[98:101], v[176:179], v[192:195], v[98:101]
	v_mfma_f32_16x16x32_bf16 v[84:87], v[168:171], v[218:221], v[84:87]
	v_mfma_f32_16x16x32_bf16 v[80:83], v[176:179], v[218:221], v[80:83]
	v_mfma_f32_16x16x32_bf16 v[68:71], v[168:171], v[226:229], v[68:71]
	v_mfma_f32_16x16x32_bf16 v[64:67], v[176:179], v[226:229], v[64:67]
	s_setprio 0
	s_barrier
	s_add_i32 s28, s60, s39
	v_lshl_add_u64 v[156:157], v[156:157], 0, s[80:81]
	s_mov_b32 m0, s28
	global_load_lds_dwordx4 v[156:157], off
	v_lshl_add_u64 v[156:157], v[230:231], 0, s[80:81]
	s_add_i32 m0, s28, 0x2000
	s_add_i32 s28, s61, s39
	global_load_lds_dwordx4 v[156:157], off
	v_lshl_add_u64 v[156:157], v[232:233], 0, s[80:81]
	s_mov_b32 m0, s28
	s_nop 0
	global_load_lds_dwordx4 v[156:157], off
	v_lshl_add_u64 v[156:157], v[234:235], 0, s[80:81]
	s_add_i32 m0, s28, 0x2000
	s_nop 0
	global_load_lds_dwordx4 v[156:157], off
	v_lshl_add_u64 v[156:157], v[236:237], 0, s[80:81]
	s_mov_b32 m0, s51
	s_nop 0
	global_load_lds_dwordx4 v[156:157], off
	v_lshl_add_u64 v[156:157], v[238:239], 0, s[80:81]
	s_mov_b32 m0, s52
	s_nop 0
	global_load_lds_dwordx4 v[156:157], off
	ds_read_b128 v[180:183], v143 offset:49152
	ds_read_b128 v[184:187], v143 offset:50176
	ds_read_b128 v[188:191], v143 offset:51200
	ds_read_b128 v[192:195], v143 offset:52224
	ds_read_b128 v[214:217], v143 offset:53248
	ds_read_b128 v[218:221], v143 offset:54272
	ds_read_b128 v[222:225], v143 offset:55296
	ds_read_b128 v[226:229], v143 offset:56320
	s_waitcnt vmcnt(8)
	s_waitcnt lgkmcnt(0)
	s_barrier
	s_setprio 1
	s_waitcnt lgkmcnt(0)
	v_mfma_f32_16x16x32_bf16 v[60:63], v[144:147], v[180:183], v[60:63]
	v_mfma_f32_16x16x32_bf16 v[56:59], v[152:155], v[180:183], v[56:59]
	v_mfma_f32_16x16x32_bf16 v[44:47], v[144:147], v[188:191], v[44:47]
	v_mfma_f32_16x16x32_bf16 v[40:43], v[152:155], v[188:191], v[40:43]
	v_mfma_f32_16x16x32_bf16 v[28:31], v[144:147], v[214:217], v[28:31]
	v_mfma_f32_16x16x32_bf16 v[24:27], v[152:155], v[214:217], v[24:27]
	v_mfma_f32_16x16x32_bf16 v[12:15], v[144:147], v[222:225], v[12:15]
	v_mfma_f32_16x16x32_bf16 v[8:11], v[152:155], v[222:225], v[8:11]
	v_mfma_f32_16x16x32_bf16 v[60:63], v[148:151], v[184:187], v[60:63]
	v_mfma_f32_16x16x32_bf16 v[56:59], v[160:163], v[184:187], v[56:59]
	v_mfma_f32_16x16x32_bf16 v[44:47], v[148:151], v[192:195], v[44:47]
	v_mfma_f32_16x16x32_bf16 v[40:43], v[160:163], v[192:195], v[40:43]
	v_mfma_f32_16x16x32_bf16 v[28:31], v[148:151], v[218:221], v[28:31]
	v_mfma_f32_16x16x32_bf16 v[24:27], v[160:163], v[218:221], v[24:27]
	v_mfma_f32_16x16x32_bf16 v[12:15], v[148:151], v[226:229], v[12:15]
	v_mfma_f32_16x16x32_bf16 v[8:11], v[160:163], v[226:229], v[8:11]
	s_setprio 0
	s_setprio 1
	v_mfma_f32_16x16x32_bf16 v[52:55], v[164:167], v[180:183], v[52:55]
	v_mfma_f32_16x16x32_bf16 v[48:51], v[172:175], v[180:183], v[48:51]
	v_mfma_f32_16x16x32_bf16 v[36:39], v[164:167], v[188:191], v[36:39]
	v_mfma_f32_16x16x32_bf16 v[32:35], v[172:175], v[188:191], v[32:35]
	v_mfma_f32_16x16x32_bf16 v[20:23], v[164:167], v[214:217], v[20:23]
	v_mfma_f32_16x16x32_bf16 v[16:19], v[172:175], v[214:217], v[16:19]
	v_mfma_f32_16x16x32_bf16 v[4:7], v[164:167], v[222:225], v[4:7]
	v_mfma_f32_16x16x32_bf16 v[0:3], v[172:175], v[222:225], v[0:3]
	v_mfma_f32_16x16x32_bf16 v[52:55], v[168:171], v[184:187], v[52:55]
	v_mfma_f32_16x16x32_bf16 v[48:51], v[176:179], v[184:187], v[48:51]
	v_mfma_f32_16x16x32_bf16 v[36:39], v[168:171], v[192:195], v[36:39]
	v_mfma_f32_16x16x32_bf16 v[32:35], v[176:179], v[192:195], v[32:35]
	v_mfma_f32_16x16x32_bf16 v[20:23], v[168:171], v[218:221], v[20:23]
	v_mfma_f32_16x16x32_bf16 v[16:19], v[176:179], v[218:221], v[16:19]
	v_mfma_f32_16x16x32_bf16 v[4:7], v[168:171], v[226:229], v[4:7]
	v_mfma_f32_16x16x32_bf16 v[0:3], v[176:179], v[226:229], v[0:3]
	s_setprio 0
	s_barrier
	s_add_u32 s26, s26, 0x100
	s_addc_u32 s27, s27, 0
	s_add_u32 s57, s57, 0x100
	s_addc_u32 s58, s58, 0
	s_cmp_ge_i32 s59, s48
	s_mov_b32 s28, s59
	s_cbranch_scc0 .LBB0_1603

.LBB0_1749:
	s_add_i32 s59, s28, 2
	s_add_u32 s60, s6, 0x80
	s_addc_u32 s29, s7, 0
	s_add_i32 s62, 0, 0x10000
	s_cmp_eq_u32 s46, s28
	s_cselect_b32 s29, s25, s29
	s_cselect_b32 s28, s24, s60
	v_add_u32_e32 v157, s62, v155
	s_cselect_b32 s61, s27, s31
	s_cselect_b32 s60, s26, s30
	s_add_i32 s63, 0, 0x14000
	ds_read_b128 v[146:149], v157
	ds_read_b128 v[150:153], v157 offset:1024
	ds_read_b128 v[160:163], v157 offset:2048
	ds_read_b128 v[164:167], v157 offset:3072
	v_add_u32_e32 v157, s63, v155
	ds_read_b128 v[168:171], v157
	ds_read_b128 v[172:175], v157 offset:1024
	ds_read_b128 v[176:179], v157 offset:2048
	ds_read_b128 v[180:183], v157 offset:3072
	v_lshl_add_u64 v[234:235], s[6:7], 0, v[142:143]
	s_add_i32 m0, s38, 0xc000
	ds_read_b128 v[184:187], v156
	ds_read_b128 v[188:191], v156 offset:1024
	ds_read_b128 v[192:195], v156 offset:2048
	ds_read_b128 v[214:217], v156 offset:3072
	ds_read_b128 v[218:221], v156 offset:4096
	ds_read_b128 v[222:225], v156 offset:5120
	ds_read_b128 v[226:229], v156 offset:6144
	ds_read_b128 v[230:233], v156 offset:7168
	global_load_lds_dwordx4 v[234:235], off
	v_lshl_add_u64 v[234:235], s[6:7], 0, v[144:145]
	s_add_i32 m0, s38, 0xe000
	s_nop 0
	global_load_lds_dwordx4 v[234:235], off
	s_waitcnt vmcnt(8)
	s_waitcnt lgkmcnt(0)
	s_barrier
	s_setprio 1
	s_waitcnt lgkmcnt(0)
	v_mfma_f32_16x16x32_bf16 v[126:129], v[146:149], v[184:187], v[126:129]
	v_mfma_f32_16x16x32_bf16 v[122:125], v[160:163], v[184:187], v[122:125]
	v_mfma_f32_16x16x32_bf16 v[118:121], v[146:149], v[192:195], v[118:121]
	v_mfma_f32_16x16x32_bf16 v[114:117], v[160:163], v[192:195], v[114:117]
	v_mfma_f32_16x16x32_bf16 v[110:113], v[146:149], v[218:221], v[110:113]
	v_mfma_f32_16x16x32_bf16 v[106:109], v[160:163], v[218:221], v[106:109]
	v_mfma_f32_16x16x32_bf16 v[102:105], v[146:149], v[226:229], v[102:105]
	v_mfma_f32_16x16x32_bf16 v[98:101], v[160:163], v[226:229], v[98:101]
	v_mfma_f32_16x16x32_bf16 v[126:129], v[150:153], v[188:191], v[126:129]
	v_mfma_f32_16x16x32_bf16 v[122:125], v[164:167], v[188:191], v[122:125]
	v_mfma_f32_16x16x32_bf16 v[118:121], v[150:153], v[214:217], v[118:121]
	v_mfma_f32_16x16x32_bf16 v[114:117], v[164:167], v[214:217], v[114:117]
	v_mfma_f32_16x16x32_bf16 v[110:113], v[150:153], v[222:225], v[110:113]
	v_mfma_f32_16x16x32_bf16 v[106:109], v[164:167], v[222:225], v[106:109]
	v_mfma_f32_16x16x32_bf16 v[102:105], v[150:153], v[230:233], v[102:105]
	v_mfma_f32_16x16x32_bf16 v[98:101], v[164:167], v[230:233], v[98:101]
	s_setprio 0
	s_setprio 1
	v_mfma_f32_16x16x32_bf16 v[60:63], v[168:171], v[184:187], v[60:63]
	v_mfma_f32_16x16x32_bf16 v[56:59], v[176:179], v[184:187], v[56:59]
	v_mfma_f32_16x16x32_bf16 v[52:55], v[168:171], v[192:195], v[52:55]
	v_mfma_f32_16x16x32_bf16 v[48:51], v[176:179], v[192:195], v[48:51]
	v_mfma_f32_16x16x32_bf16 v[44:47], v[168:171], v[218:221], v[44:47]
	v_mfma_f32_16x16x32_bf16 v[40:43], v[176:179], v[218:221], v[40:43]
	v_mfma_f32_16x16x32_bf16 v[36:39], v[168:171], v[226:229], v[36:39]
	v_mfma_f32_16x16x32_bf16 v[32:35], v[176:179], v[226:229], v[32:35]
	v_mfma_f32_16x16x32_bf16 v[60:63], v[172:175], v[188:191], v[60:63]
	v_mfma_f32_16x16x32_bf16 v[56:59], v[180:183], v[188:191], v[56:59]
	v_mfma_f32_16x16x32_bf16 v[52:55], v[172:175], v[214:217], v[52:55]
	v_mfma_f32_16x16x32_bf16 v[48:51], v[180:183], v[214:217], v[48:51]
	v_mfma_f32_16x16x32_bf16 v[44:47], v[172:175], v[222:225], v[44:47]
	v_mfma_f32_16x16x32_bf16 v[40:43], v[180:183], v[222:225], v[40:43]
	v_mfma_f32_16x16x32_bf16 v[36:39], v[172:175], v[230:233], v[36:39]
	v_mfma_f32_16x16x32_bf16 v[32:35], v[180:183], v[230:233], v[32:35]
	s_setprio 0
	s_barrier
	s_add_i32 s62, s62, s37
	v_lshl_add_u64 v[234:235], s[60:61], 0, v[92:93]
	s_mov_b32 m0, s62
	global_load_lds_dwordx4 v[234:235], off
	s_add_i32 m0, s62, 0x2000
	v_lshl_add_u64 v[236:237], s[60:61], 0, v[134:135]
	s_add_u32 s60, s60, s8
	s_addc_u32 s61, s61, s9
	s_add_i32 s62, s63, s37
	global_load_lds_dwordx4 v[236:237], off
	v_lshl_add_u64 v[238:239], s[60:61], 0, v[92:93]
	s_mov_b32 m0, s62
	v_lshl_add_u64 v[240:241], s[60:61], 0, v[134:135]
	global_load_lds_dwordx4 v[238:239], off
	s_add_i32 m0, s62, 0x2000
	v_lshl_add_u64 v[242:243], s[28:29], 0, v[130:131]
	global_load_lds_dwordx4 v[240:241], off
	s_mov_b32 m0, s38
	v_lshl_add_u64 v[244:245], s[28:29], 0, v[132:133]
	global_load_lds_dwordx4 v[242:243], off
	s_mov_b32 m0, s39
	s_nop 0
	global_load_lds_dwordx4 v[244:245], off
	ds_read_b128 v[184:187], v156 offset:16384
	ds_read_b128 v[188:191], v156 offset:17408
	ds_read_b128 v[192:195], v156 offset:18432
	ds_read_b128 v[214:217], v156 offset:19456
	ds_read_b128 v[218:221], v156 offset:20480
	ds_read_b128 v[222:225], v156 offset:21504
	ds_read_b128 v[226:229], v156 offset:22528
	ds_read_b128 v[230:233], v156 offset:23552
	s_waitcnt vmcnt(8)
	s_waitcnt lgkmcnt(0)
	s_barrier
	s_setprio 1
	s_waitcnt lgkmcnt(0)
	v_mfma_f32_16x16x32_bf16 v[94:97], v[146:149], v[184:187], v[94:97]
	v_mfma_f32_16x16x32_bf16 v[88:91], v[160:163], v[184:187], v[88:91]
	v_mfma_f32_16x16x32_bf16 v[84:87], v[146:149], v[192:195], v[84:87]
	v_mfma_f32_16x16x32_bf16 v[80:83], v[160:163], v[192:195], v[80:83]
	v_mfma_f32_16x16x32_bf16 v[76:79], v[146:149], v[218:221], v[76:79]
	v_mfma_f32_16x16x32_bf16 v[72:75], v[160:163], v[218:221], v[72:75]
	v_mfma_f32_16x16x32_bf16 v[68:71], v[146:149], v[226:229], v[68:71]
	v_mfma_f32_16x16x32_bf16 v[64:67], v[160:163], v[226:229], v[64:67]
	v_mfma_f32_16x16x32_bf16 v[94:97], v[150:153], v[188:191], v[94:97]
	v_mfma_f32_16x16x32_bf16 v[88:91], v[164:167], v[188:191], v[88:91]
	v_mfma_f32_16x16x32_bf16 v[84:87], v[150:153], v[214:217], v[84:87]
	v_mfma_f32_16x16x32_bf16 v[80:83], v[164:167], v[214:217], v[80:83]
	v_mfma_f32_16x16x32_bf16 v[76:79], v[150:153], v[222:225], v[76:79]
	v_mfma_f32_16x16x32_bf16 v[72:75], v[164:167], v[222:225], v[72:75]
	v_mfma_f32_16x16x32_bf16 v[68:71], v[150:153], v[230:233], v[68:71]
	v_mfma_f32_16x16x32_bf16 v[64:67], v[164:167], v[230:233], v[64:67]
	s_setprio 0
	s_setprio 1
	v_mfma_f32_16x16x32_bf16 v[28:31], v[168:171], v[184:187], v[28:31]
	v_mfma_f32_16x16x32_bf16 v[24:27], v[176:179], v[184:187], v[24:27]
	v_mfma_f32_16x16x32_bf16 v[20:23], v[168:171], v[192:195], v[20:23]
	v_mfma_f32_16x16x32_bf16 v[16:19], v[176:179], v[192:195], v[16:19]
	v_mfma_f32_16x16x32_bf16 v[12:15], v[168:171], v[218:221], v[12:15]
	v_mfma_f32_16x16x32_bf16 v[8:11], v[176:179], v[218:221], v[8:11]
	v_mfma_f32_16x16x32_bf16 v[4:7], v[168:171], v[226:229], v[4:7]
	v_mfma_f32_16x16x32_bf16 v[0:3], v[176:179], v[226:229], v[0:3]
	v_mfma_f32_16x16x32_bf16 v[28:31], v[172:175], v[188:191], v[28:31]
	v_mfma_f32_16x16x32_bf16 v[24:27], v[180:183], v[188:191], v[24:27]
	v_mfma_f32_16x16x32_bf16 v[20:23], v[172:175], v[214:217], v[20:23]
	v_mfma_f32_16x16x32_bf16 v[16:19], v[180:183], v[214:217], v[16:19]
	v_mfma_f32_16x16x32_bf16 v[12:15], v[172:175], v[222:225], v[12:15]
	v_mfma_f32_16x16x32_bf16 v[8:11], v[180:183], v[222:225], v[8:11]
	v_mfma_f32_16x16x32_bf16 v[4:7], v[172:175], v[230:233], v[4:7]
	v_mfma_f32_16x16x32_bf16 v[0:3], v[180:183], v[230:233], v[0:3]
	s_setprio 0
	s_barrier
	s_add_i32 s60, 0, 0x18000
	v_add_u32_e32 v157, s60, v155
	s_add_i32 s61, 0, 0x1c000
	ds_read_b128 v[146:149], v157
	ds_read_b128 v[150:153], v157 offset:1024
	ds_read_b128 v[160:163], v157 offset:2048
	ds_read_b128 v[164:167], v157 offset:3072
	v_add_u32_e32 v157, s61, v155
	ds_read_b128 v[168:171], v157
	ds_read_b128 v[172:175], v157 offset:1024
	ds_read_b128 v[176:179], v157 offset:2048
	ds_read_b128 v[180:183], v157 offset:3072
	s_add_u32 s28, s28, s12
	s_addc_u32 s29, s29, s13
	s_mov_b32 m0, s40
	v_lshl_add_u64 v[246:247], s[28:29], 0, v[130:131]
	ds_read_b128 v[184:187], v156 offset:32768
	ds_read_b128 v[188:191], v156 offset:33792
	ds_read_b128 v[192:195], v156 offset:34816
	ds_read_b128 v[214:217], v156 offset:35840
	ds_read_b128 v[218:221], v156 offset:36864
	ds_read_b128 v[222:225], v156 offset:37888
	ds_read_b128 v[226:229], v156 offset:38912
	ds_read_b128 v[230:233], v156 offset:39936
	global_load_lds_dwordx4 v[246:247], off
	v_lshl_add_u64 v[246:247], s[28:29], 0, v[132:133]
	s_mov_b32 m0, s41
	s_nop 0
	global_load_lds_dwordx4 v[246:247], off
	s_waitcnt vmcnt(8)
	s_waitcnt lgkmcnt(0)
	s_barrier
	s_setprio 1
	s_waitcnt lgkmcnt(0)
	v_mfma_f32_16x16x32_bf16 v[126:129], v[146:149], v[184:187], v[126:129]
	v_mfma_f32_16x16x32_bf16 v[122:125], v[160:163], v[184:187], v[122:125]
	v_mfma_f32_16x16x32_bf16 v[118:121], v[146:149], v[192:195], v[118:121]
	v_mfma_f32_16x16x32_bf16 v[114:117], v[160:163], v[192:195], v[114:117]
	v_mfma_f32_16x16x32_bf16 v[110:113], v[146:149], v[218:221], v[110:113]
	v_mfma_f32_16x16x32_bf16 v[106:109], v[160:163], v[218:221], v[106:109]
	v_mfma_f32_16x16x32_bf16 v[102:105], v[146:149], v[226:229], v[102:105]
	v_mfma_f32_16x16x32_bf16 v[98:101], v[160:163], v[226:229], v[98:101]
	v_mfma_f32_16x16x32_bf16 v[126:129], v[150:153], v[188:191], v[126:129]
	v_mfma_f32_16x16x32_bf16 v[122:125], v[164:167], v[188:191], v[122:125]
	v_mfma_f32_16x16x32_bf16 v[118:121], v[150:153], v[214:217], v[118:121]
	v_mfma_f32_16x16x32_bf16 v[114:117], v[164:167], v[214:217], v[114:117]
	v_mfma_f32_16x16x32_bf16 v[110:113], v[150:153], v[222:225], v[110:113]
	v_mfma_f32_16x16x32_bf16 v[106:109], v[164:167], v[222:225], v[106:109]
	v_mfma_f32_16x16x32_bf16 v[102:105], v[150:153], v[230:233], v[102:105]
	v_mfma_f32_16x16x32_bf16 v[98:101], v[164:167], v[230:233], v[98:101]
	s_setprio 0
	s_setprio 1
	v_mfma_f32_16x16x32_bf16 v[60:63], v[168:171], v[184:187], v[60:63]
	v_mfma_f32_16x16x32_bf16 v[56:59], v[176:179], v[184:187], v[56:59]
	v_mfma_f32_16x16x32_bf16 v[52:55], v[168:171], v[192:195], v[52:55]
	v_mfma_f32_16x16x32_bf16 v[48:51], v[176:179], v[192:195], v[48:51]
	v_mfma_f32_16x16x32_bf16 v[44:47], v[168:171], v[218:221], v[44:47]
	v_mfma_f32_16x16x32_bf16 v[40:43], v[176:179], v[218:221], v[40:43]
	v_mfma_f32_16x16x32_bf16 v[36:39], v[168:171], v[226:229], v[36:39]
	v_mfma_f32_16x16x32_bf16 v[32:35], v[176:179], v[226:229], v[32:35]
	v_mfma_f32_16x16x32_bf16 v[60:63], v[172:175], v[188:191], v[60:63]
	v_mfma_f32_16x16x32_bf16 v[56:59], v[180:183], v[188:191], v[56:59]
	v_mfma_f32_16x16x32_bf16 v[52:55], v[172:175], v[214:217], v[52:55]
	v_mfma_f32_16x16x32_bf16 v[48:51], v[180:183], v[214:217], v[48:51]
	v_mfma_f32_16x16x32_bf16 v[44:47], v[172:175], v[222:225], v[44:47]
	v_mfma_f32_16x16x32_bf16 v[40:43], v[180:183], v[222:225], v[40:43]
	v_mfma_f32_16x16x32_bf16 v[36:39], v[172:175], v[230:233], v[36:39]
	v_mfma_f32_16x16x32_bf16 v[32:35], v[180:183], v[230:233], v[32:35]
	s_setprio 0
	s_barrier
	s_add_i32 s28, s60, s37
	v_lshl_add_u64 v[234:235], v[234:235], 0, s[80:81]
	s_mov_b32 m0, s28
	global_load_lds_dwordx4 v[234:235], off
	v_lshl_add_u64 v[234:235], v[236:237], 0, s[80:81]
	s_add_i32 m0, s28, 0x2000
	s_add_i32 s28, s61, s37
	global_load_lds_dwordx4 v[234:235], off
	v_lshl_add_u64 v[234:235], v[238:239], 0, s[80:81]
	s_mov_b32 m0, s28
	s_nop 0
	global_load_lds_dwordx4 v[234:235], off
	v_lshl_add_u64 v[234:235], v[240:241], 0, s[80:81]
	s_add_i32 m0, s28, 0x2000
	s_nop 0
	global_load_lds_dwordx4 v[234:235], off
	v_lshl_add_u64 v[234:235], v[242:243], 0, s[80:81]
	s_mov_b32 m0, s42
	s_nop 0
	global_load_lds_dwordx4 v[234:235], off
	v_lshl_add_u64 v[234:235], v[244:245], 0, s[80:81]
	s_mov_b32 m0, s43
	s_nop 0
	global_load_lds_dwordx4 v[234:235], off
	ds_read_b128 v[184:187], v156 offset:49152
	ds_read_b128 v[188:191], v156 offset:50176
	ds_read_b128 v[192:195], v156 offset:51200
	ds_read_b128 v[214:217], v156 offset:52224
	ds_read_b128 v[218:221], v156 offset:53248
	ds_read_b128 v[222:225], v156 offset:54272
	ds_read_b128 v[226:229], v156 offset:55296
	ds_read_b128 v[230:233], v156 offset:56320
	s_waitcnt vmcnt(8)
	s_waitcnt lgkmcnt(0)
	s_barrier
	s_setprio 1
	s_waitcnt lgkmcnt(0)
	v_mfma_f32_16x16x32_bf16 v[94:97], v[146:149], v[184:187], v[94:97]
	v_mfma_f32_16x16x32_bf16 v[88:91], v[160:163], v[184:187], v[88:91]
	v_mfma_f32_16x16x32_bf16 v[84:87], v[146:149], v[192:195], v[84:87]
	v_mfma_f32_16x16x32_bf16 v[80:83], v[160:163], v[192:195], v[80:83]
	v_mfma_f32_16x16x32_bf16 v[76:79], v[146:149], v[218:221], v[76:79]
	v_mfma_f32_16x16x32_bf16 v[72:75], v[160:163], v[218:221], v[72:75]
	v_mfma_f32_16x16x32_bf16 v[68:71], v[146:149], v[226:229], v[68:71]
	v_mfma_f32_16x16x32_bf16 v[64:67], v[160:163], v[226:229], v[64:67]
	v_mfma_f32_16x16x32_bf16 v[94:97], v[150:153], v[188:191], v[94:97]
	v_mfma_f32_16x16x32_bf16 v[88:91], v[164:167], v[188:191], v[88:91]
	v_mfma_f32_16x16x32_bf16 v[84:87], v[150:153], v[214:217], v[84:87]
	v_mfma_f32_16x16x32_bf16 v[80:83], v[164:167], v[214:217], v[80:83]
	v_mfma_f32_16x16x32_bf16 v[76:79], v[150:153], v[222:225], v[76:79]
	v_mfma_f32_16x16x32_bf16 v[72:75], v[164:167], v[222:225], v[72:75]
	v_mfma_f32_16x16x32_bf16 v[68:71], v[150:153], v[230:233], v[68:71]
	v_mfma_f32_16x16x32_bf16 v[64:67], v[164:167], v[230:233], v[64:67]
	s_setprio 0
	s_setprio 1
	v_mfma_f32_16x16x32_bf16 v[28:31], v[168:171], v[184:187], v[28:31]
	v_mfma_f32_16x16x32_bf16 v[24:27], v[176:179], v[184:187], v[24:27]
	v_mfma_f32_16x16x32_bf16 v[20:23], v[168:171], v[192:195], v[20:23]
	v_mfma_f32_16x16x32_bf16 v[16:19], v[176:179], v[192:195], v[16:19]
	v_mfma_f32_16x16x32_bf16 v[12:15], v[168:171], v[218:221], v[12:15]
	v_mfma_f32_16x16x32_bf16 v[8:11], v[176:179], v[218:221], v[8:11]
	v_mfma_f32_16x16x32_bf16 v[4:7], v[168:171], v[226:229], v[4:7]
	v_mfma_f32_16x16x32_bf16 v[0:3], v[176:179], v[226:229], v[0:3]
	v_mfma_f32_16x16x32_bf16 v[28:31], v[172:175], v[188:191], v[28:31]
	v_mfma_f32_16x16x32_bf16 v[24:27], v[180:183], v[188:191], v[24:27]
	v_mfma_f32_16x16x32_bf16 v[20:23], v[172:175], v[214:217], v[20:23]
	v_mfma_f32_16x16x32_bf16 v[16:19], v[180:183], v[214:217], v[16:19]
	v_mfma_f32_16x16x32_bf16 v[12:15], v[172:175], v[222:225], v[12:15]
	v_mfma_f32_16x16x32_bf16 v[8:11], v[180:183], v[222:225], v[8:11]
	v_mfma_f32_16x16x32_bf16 v[4:7], v[172:175], v[230:233], v[4:7]
	v_mfma_f32_16x16x32_bf16 v[0:3], v[180:183], v[230:233], v[0:3]
	s_setprio 0
	s_barrier
	s_add_u32 s6, s6, 0x100
	s_addc_u32 s7, s7, 0
	s_add_u32 s30, s30, 0x100
	s_addc_u32 s31, s31, 0
	s_cmp_ge_i32 s59, s44
	s_mov_b32 s28, s59
	s_cbranch_scc0 .LBB0_1749

.LBB0_1812:
	s_add_i32 s60, s30, 2
	s_add_u32 s61, s6, 0x80
	s_addc_u32 s31, s7, 0
	s_add_i32 s64, 0, 0x10000
	s_cmp_eq_u32 s47, s30
	s_cselect_b32 s31, s27, s31
	s_cselect_b32 s30, s26, s61
	v_add_u32_e32 v92, s64, v150
	s_cselect_b32 s63, s29, s35
	s_cselect_b32 s62, s28, s34
	s_add_i32 s61, 0, 0x14000
	ds_read_b128 v[146:149], v92
	ds_read_b128 v[152:155], v92 offset:1024
	ds_read_b128 v[160:163], v92 offset:2048
	ds_read_b128 v[164:167], v92 offset:3072
	v_add_u32_e32 v92, s61, v150
	ds_read_b128 v[168:171], v92
	ds_read_b128 v[172:175], v92 offset:1024
	ds_read_b128 v[176:179], v92 offset:2048
	ds_read_b128 v[180:183], v92 offset:3072
	v_lshl_add_u64 v[156:157], s[6:7], 0, v[142:143]
	s_add_i32 m0, s40, 0xc000
	ds_read_b128 v[184:187], v151
	ds_read_b128 v[188:191], v151 offset:1024
	ds_read_b128 v[192:195], v151 offset:2048
	ds_read_b128 v[214:217], v151 offset:3072
	ds_read_b128 v[218:221], v151 offset:4096
	ds_read_b128 v[222:225], v151 offset:5120
	ds_read_b128 v[226:229], v151 offset:6144
	ds_read_b128 v[230:233], v151 offset:7168
	global_load_lds_dwordx4 v[156:157], off
	v_lshl_add_u64 v[156:157], s[6:7], 0, v[144:145]
	s_add_i32 m0, s40, 0xe000
	s_nop 0
	global_load_lds_dwordx4 v[156:157], off
	s_waitcnt vmcnt(8)
	s_waitcnt lgkmcnt(0)
	s_barrier
	s_setprio 1
	s_waitcnt lgkmcnt(0)
	v_mfma_f32_16x16x32_bf16 v[126:129], v[146:149], v[184:187], v[126:129]
	v_mfma_f32_16x16x32_bf16 v[122:125], v[160:163], v[184:187], v[122:125]
	v_mfma_f32_16x16x32_bf16 v[118:121], v[146:149], v[192:195], v[118:121]
	v_mfma_f32_16x16x32_bf16 v[114:117], v[160:163], v[192:195], v[114:117]
	v_mfma_f32_16x16x32_bf16 v[110:113], v[146:149], v[218:221], v[110:113]
	v_mfma_f32_16x16x32_bf16 v[106:109], v[160:163], v[218:221], v[106:109]
	v_mfma_f32_16x16x32_bf16 v[102:105], v[146:149], v[226:229], v[102:105]
	v_mfma_f32_16x16x32_bf16 v[98:101], v[160:163], v[226:229], v[98:101]
	v_mfma_f32_16x16x32_bf16 v[126:129], v[152:155], v[188:191], v[126:129]
	v_mfma_f32_16x16x32_bf16 v[122:125], v[164:167], v[188:191], v[122:125]
	v_mfma_f32_16x16x32_bf16 v[118:121], v[152:155], v[214:217], v[118:121]
	v_mfma_f32_16x16x32_bf16 v[114:117], v[164:167], v[214:217], v[114:117]
	v_mfma_f32_16x16x32_bf16 v[110:113], v[152:155], v[222:225], v[110:113]
	v_mfma_f32_16x16x32_bf16 v[106:109], v[164:167], v[222:225], v[106:109]
	v_mfma_f32_16x16x32_bf16 v[102:105], v[152:155], v[230:233], v[102:105]
	v_mfma_f32_16x16x32_bf16 v[98:101], v[164:167], v[230:233], v[98:101]
	s_setprio 0
	s_setprio 1
	v_mfma_f32_16x16x32_bf16 v[60:63], v[168:171], v[184:187], v[60:63]
	v_mfma_f32_16x16x32_bf16 v[56:59], v[176:179], v[184:187], v[56:59]
	v_mfma_f32_16x16x32_bf16 v[52:55], v[168:171], v[192:195], v[52:55]
	v_mfma_f32_16x16x32_bf16 v[48:51], v[176:179], v[192:195], v[48:51]
	v_mfma_f32_16x16x32_bf16 v[44:47], v[168:171], v[218:221], v[44:47]
	v_mfma_f32_16x16x32_bf16 v[40:43], v[176:179], v[218:221], v[40:43]
	v_mfma_f32_16x16x32_bf16 v[36:39], v[168:171], v[226:229], v[36:39]
	v_mfma_f32_16x16x32_bf16 v[32:35], v[176:179], v[226:229], v[32:35]
	v_mfma_f32_16x16x32_bf16 v[60:63], v[172:175], v[188:191], v[60:63]
	v_mfma_f32_16x16x32_bf16 v[56:59], v[180:183], v[188:191], v[56:59]
	v_mfma_f32_16x16x32_bf16 v[52:55], v[172:175], v[214:217], v[52:55]
	v_mfma_f32_16x16x32_bf16 v[48:51], v[180:183], v[214:217], v[48:51]
	v_mfma_f32_16x16x32_bf16 v[44:47], v[172:175], v[222:225], v[44:47]
	v_mfma_f32_16x16x32_bf16 v[40:43], v[180:183], v[222:225], v[40:43]
	v_mfma_f32_16x16x32_bf16 v[36:39], v[172:175], v[230:233], v[36:39]
	v_mfma_f32_16x16x32_bf16 v[32:35], v[180:183], v[230:233], v[32:35]
	s_setprio 0
	s_barrier
	s_add_i32 s64, s64, s39
	v_lshl_add_u64 v[156:157], s[62:63], 0, v[132:133]
	s_mov_b32 m0, s64
	global_load_lds_dwordx4 v[156:157], off
	s_add_i32 m0, s64, 0x2000
	v_lshl_add_u64 v[234:235], s[62:63], 0, v[136:137]
	s_add_u32 s62, s62, s8
	s_addc_u32 s63, s63, s9
	s_add_i32 s61, s61, s39
	global_load_lds_dwordx4 v[234:235], off
	v_lshl_add_u64 v[236:237], s[62:63], 0, v[132:133]
	s_mov_b32 m0, s61
	v_lshl_add_u64 v[238:239], s[62:63], 0, v[136:137]
	global_load_lds_dwordx4 v[236:237], off
	s_add_i32 m0, s61, 0x2000
	v_lshl_add_u64 v[240:241], s[30:31], 0, v[130:131]
	global_load_lds_dwordx4 v[238:239], off
	s_mov_b32 m0, s40
	v_lshl_add_u64 v[242:243], s[30:31], 0, v[134:135]
	global_load_lds_dwordx4 v[240:241], off
	s_mov_b32 m0, s41
	s_nop 0
	global_load_lds_dwordx4 v[242:243], off
	ds_read_b128 v[184:187], v151 offset:16384
	ds_read_b128 v[188:191], v151 offset:17408
	ds_read_b128 v[192:195], v151 offset:18432
	ds_read_b128 v[214:217], v151 offset:19456
	ds_read_b128 v[218:221], v151 offset:20480
	ds_read_b128 v[222:225], v151 offset:21504
	ds_read_b128 v[226:229], v151 offset:22528
	ds_read_b128 v[230:233], v151 offset:23552
	s_waitcnt vmcnt(8)
	s_waitcnt lgkmcnt(0)
	s_barrier
	s_setprio 1
	s_waitcnt lgkmcnt(0)
	v_mfma_f32_16x16x32_bf16 v[94:97], v[146:149], v[184:187], v[94:97]
	v_mfma_f32_16x16x32_bf16 v[88:91], v[160:163], v[184:187], v[88:91]
	v_mfma_f32_16x16x32_bf16 v[84:87], v[146:149], v[192:195], v[84:87]
	v_mfma_f32_16x16x32_bf16 v[80:83], v[160:163], v[192:195], v[80:83]
	v_mfma_f32_16x16x32_bf16 v[76:79], v[146:149], v[218:221], v[76:79]
	v_mfma_f32_16x16x32_bf16 v[72:75], v[160:163], v[218:221], v[72:75]
	v_mfma_f32_16x16x32_bf16 v[68:71], v[146:149], v[226:229], v[68:71]
	v_mfma_f32_16x16x32_bf16 v[64:67], v[160:163], v[226:229], v[64:67]
	v_mfma_f32_16x16x32_bf16 v[94:97], v[152:155], v[188:191], v[94:97]
	v_mfma_f32_16x16x32_bf16 v[88:91], v[164:167], v[188:191], v[88:91]
	v_mfma_f32_16x16x32_bf16 v[84:87], v[152:155], v[214:217], v[84:87]
	v_mfma_f32_16x16x32_bf16 v[80:83], v[164:167], v[214:217], v[80:83]
	v_mfma_f32_16x16x32_bf16 v[76:79], v[152:155], v[222:225], v[76:79]
	v_mfma_f32_16x16x32_bf16 v[72:75], v[164:167], v[222:225], v[72:75]
	v_mfma_f32_16x16x32_bf16 v[68:71], v[152:155], v[230:233], v[68:71]
	v_mfma_f32_16x16x32_bf16 v[64:67], v[164:167], v[230:233], v[64:67]
	s_setprio 0
	s_setprio 1
	v_mfma_f32_16x16x32_bf16 v[28:31], v[168:171], v[184:187], v[28:31]
	v_mfma_f32_16x16x32_bf16 v[24:27], v[176:179], v[184:187], v[24:27]
	v_mfma_f32_16x16x32_bf16 v[20:23], v[168:171], v[192:195], v[20:23]
	v_mfma_f32_16x16x32_bf16 v[16:19], v[176:179], v[192:195], v[16:19]
	v_mfma_f32_16x16x32_bf16 v[12:15], v[168:171], v[218:221], v[12:15]
	v_mfma_f32_16x16x32_bf16 v[8:11], v[176:179], v[218:221], v[8:11]
	v_mfma_f32_16x16x32_bf16 v[4:7], v[168:171], v[226:229], v[4:7]
	v_mfma_f32_16x16x32_bf16 v[0:3], v[176:179], v[226:229], v[0:3]
	v_mfma_f32_16x16x32_bf16 v[28:31], v[172:175], v[188:191], v[28:31]
	v_mfma_f32_16x16x32_bf16 v[24:27], v[180:183], v[188:191], v[24:27]
	v_mfma_f32_16x16x32_bf16 v[20:23], v[172:175], v[214:217], v[20:23]
	v_mfma_f32_16x16x32_bf16 v[16:19], v[180:183], v[214:217], v[16:19]
	v_mfma_f32_16x16x32_bf16 v[12:15], v[172:175], v[222:225], v[12:15]
	v_mfma_f32_16x16x32_bf16 v[8:11], v[180:183], v[222:225], v[8:11]
	v_mfma_f32_16x16x32_bf16 v[4:7], v[172:175], v[230:233], v[4:7]
	v_mfma_f32_16x16x32_bf16 v[0:3], v[180:183], v[230:233], v[0:3]
	s_setprio 0
	s_barrier
	s_add_i32 s61, 0, 0x18000
	v_add_u32_e32 v92, s61, v150
	s_add_i32 s62, 0, 0x1c000
	ds_read_b128 v[146:149], v92
	ds_read_b128 v[152:155], v92 offset:1024
	ds_read_b128 v[160:163], v92 offset:2048
	ds_read_b128 v[164:167], v92 offset:3072
	v_add_u32_e32 v92, s62, v150
	ds_read_b128 v[168:171], v92
	ds_read_b128 v[172:175], v92 offset:1024
	ds_read_b128 v[176:179], v92 offset:2048
	ds_read_b128 v[180:183], v92 offset:3072
	s_add_u32 s30, s30, s12
	s_addc_u32 s31, s31, s13
	s_mov_b32 m0, s42
	v_lshl_add_u64 v[244:245], s[30:31], 0, v[130:131]
	ds_read_b128 v[184:187], v151 offset:32768
	ds_read_b128 v[188:191], v151 offset:33792
	ds_read_b128 v[192:195], v151 offset:34816
	ds_read_b128 v[214:217], v151 offset:35840
	ds_read_b128 v[218:221], v151 offset:36864
	ds_read_b128 v[222:225], v151 offset:37888
	ds_read_b128 v[226:229], v151 offset:38912
	ds_read_b128 v[230:233], v151 offset:39936
	global_load_lds_dwordx4 v[244:245], off
	v_lshl_add_u64 v[244:245], s[30:31], 0, v[134:135]
	s_mov_b32 m0, s43
	s_nop 0
	global_load_lds_dwordx4 v[244:245], off
	s_waitcnt vmcnt(8)
	s_waitcnt lgkmcnt(0)
	s_barrier
	s_setprio 1
	s_waitcnt lgkmcnt(0)
	v_mfma_f32_16x16x32_bf16 v[126:129], v[146:149], v[184:187], v[126:129]
	v_mfma_f32_16x16x32_bf16 v[122:125], v[160:163], v[184:187], v[122:125]
	v_mfma_f32_16x16x32_bf16 v[118:121], v[146:149], v[192:195], v[118:121]
	v_mfma_f32_16x16x32_bf16 v[114:117], v[160:163], v[192:195], v[114:117]
	v_mfma_f32_16x16x32_bf16 v[110:113], v[146:149], v[218:221], v[110:113]
	v_mfma_f32_16x16x32_bf16 v[106:109], v[160:163], v[218:221], v[106:109]
	v_mfma_f32_16x16x32_bf16 v[102:105], v[146:149], v[226:229], v[102:105]
	v_mfma_f32_16x16x32_bf16 v[98:101], v[160:163], v[226:229], v[98:101]
	v_mfma_f32_16x16x32_bf16 v[126:129], v[152:155], v[188:191], v[126:129]
	v_mfma_f32_16x16x32_bf16 v[122:125], v[164:167], v[188:191], v[122:125]
	v_mfma_f32_16x16x32_bf16 v[118:121], v[152:155], v[214:217], v[118:121]
	v_mfma_f32_16x16x32_bf16 v[114:117], v[164:167], v[214:217], v[114:117]
	v_mfma_f32_16x16x32_bf16 v[110:113], v[152:155], v[222:225], v[110:113]
	v_mfma_f32_16x16x32_bf16 v[106:109], v[164:167], v[222:225], v[106:109]
	v_mfma_f32_16x16x32_bf16 v[102:105], v[152:155], v[230:233], v[102:105]
	v_mfma_f32_16x16x32_bf16 v[98:101], v[164:167], v[230:233], v[98:101]
	s_setprio 0
	s_setprio 1
	v_mfma_f32_16x16x32_bf16 v[60:63], v[168:171], v[184:187], v[60:63]
	v_mfma_f32_16x16x32_bf16 v[56:59], v[176:179], v[184:187], v[56:59]
	v_mfma_f32_16x16x32_bf16 v[52:55], v[168:171], v[192:195], v[52:55]
	v_mfma_f32_16x16x32_bf16 v[48:51], v[176:179], v[192:195], v[48:51]
	v_mfma_f32_16x16x32_bf16 v[44:47], v[168:171], v[218:221], v[44:47]
	v_mfma_f32_16x16x32_bf16 v[40:43], v[176:179], v[218:221], v[40:43]
	v_mfma_f32_16x16x32_bf16 v[36:39], v[168:171], v[226:229], v[36:39]
	v_mfma_f32_16x16x32_bf16 v[32:35], v[176:179], v[226:229], v[32:35]
	v_mfma_f32_16x16x32_bf16 v[60:63], v[172:175], v[188:191], v[60:63]
	v_mfma_f32_16x16x32_bf16 v[56:59], v[180:183], v[188:191], v[56:59]
	v_mfma_f32_16x16x32_bf16 v[52:55], v[172:175], v[214:217], v[52:55]
	v_mfma_f32_16x16x32_bf16 v[48:51], v[180:183], v[214:217], v[48:51]
	v_mfma_f32_16x16x32_bf16 v[44:47], v[172:175], v[222:225], v[44:47]
	v_mfma_f32_16x16x32_bf16 v[40:43], v[180:183], v[222:225], v[40:43]
	v_mfma_f32_16x16x32_bf16 v[36:39], v[172:175], v[230:233], v[36:39]
	v_mfma_f32_16x16x32_bf16 v[32:35], v[180:183], v[230:233], v[32:35]
	s_setprio 0
	s_barrier
	s_add_i32 s30, s61, s39
	v_lshl_add_u64 v[156:157], v[156:157], 0, s[80:81]
	s_mov_b32 m0, s30
	global_load_lds_dwordx4 v[156:157], off
	v_lshl_add_u64 v[156:157], v[234:235], 0, s[80:81]
	s_add_i32 m0, s30, 0x2000
	s_add_i32 s30, s62, s39
	global_load_lds_dwordx4 v[156:157], off
	v_lshl_add_u64 v[156:157], v[236:237], 0, s[80:81]
	s_mov_b32 m0, s30
	s_nop 0
	global_load_lds_dwordx4 v[156:157], off
	v_lshl_add_u64 v[156:157], v[238:239], 0, s[80:81]
	s_add_i32 m0, s30, 0x2000
	s_nop 0
	global_load_lds_dwordx4 v[156:157], off
	v_lshl_add_u64 v[156:157], v[240:241], 0, s[80:81]
	s_mov_b32 m0, s45
	s_nop 0
	global_load_lds_dwordx4 v[156:157], off
	v_lshl_add_u64 v[156:157], v[242:243], 0, s[80:81]
	s_mov_b32 m0, s46
	s_nop 0
	global_load_lds_dwordx4 v[156:157], off
	ds_read_b128 v[184:187], v151 offset:49152
	ds_read_b128 v[188:191], v151 offset:50176
	ds_read_b128 v[192:195], v151 offset:51200
	ds_read_b128 v[214:217], v151 offset:52224
	ds_read_b128 v[218:221], v151 offset:53248
	ds_read_b128 v[222:225], v151 offset:54272
	ds_read_b128 v[226:229], v151 offset:55296
	ds_read_b128 v[230:233], v151 offset:56320
	s_waitcnt vmcnt(8)
	s_waitcnt lgkmcnt(0)
	s_barrier
	s_setprio 1
	s_waitcnt lgkmcnt(0)
	v_mfma_f32_16x16x32_bf16 v[94:97], v[146:149], v[184:187], v[94:97]
	v_mfma_f32_16x16x32_bf16 v[88:91], v[160:163], v[184:187], v[88:91]
	v_mfma_f32_16x16x32_bf16 v[84:87], v[146:149], v[192:195], v[84:87]
	v_mfma_f32_16x16x32_bf16 v[80:83], v[160:163], v[192:195], v[80:83]
	v_mfma_f32_16x16x32_bf16 v[76:79], v[146:149], v[218:221], v[76:79]
	v_mfma_f32_16x16x32_bf16 v[72:75], v[160:163], v[218:221], v[72:75]
	v_mfma_f32_16x16x32_bf16 v[68:71], v[146:149], v[226:229], v[68:71]
	v_mfma_f32_16x16x32_bf16 v[64:67], v[160:163], v[226:229], v[64:67]
	v_mfma_f32_16x16x32_bf16 v[94:97], v[152:155], v[188:191], v[94:97]
	v_mfma_f32_16x16x32_bf16 v[88:91], v[164:167], v[188:191], v[88:91]
	v_mfma_f32_16x16x32_bf16 v[84:87], v[152:155], v[214:217], v[84:87]
	v_mfma_f32_16x16x32_bf16 v[80:83], v[164:167], v[214:217], v[80:83]
	v_mfma_f32_16x16x32_bf16 v[76:79], v[152:155], v[222:225], v[76:79]
	v_mfma_f32_16x16x32_bf16 v[72:75], v[164:167], v[222:225], v[72:75]
	v_mfma_f32_16x16x32_bf16 v[68:71], v[152:155], v[230:233], v[68:71]
	v_mfma_f32_16x16x32_bf16 v[64:67], v[164:167], v[230:233], v[64:67]
	s_setprio 0
	s_setprio 1
	v_mfma_f32_16x16x32_bf16 v[28:31], v[168:171], v[184:187], v[28:31]
	v_mfma_f32_16x16x32_bf16 v[24:27], v[176:179], v[184:187], v[24:27]
	v_mfma_f32_16x16x32_bf16 v[20:23], v[168:171], v[192:195], v[20:23]
	v_mfma_f32_16x16x32_bf16 v[16:19], v[176:179], v[192:195], v[16:19]
	v_mfma_f32_16x16x32_bf16 v[12:15], v[168:171], v[218:221], v[12:15]
	v_mfma_f32_16x16x32_bf16 v[8:11], v[176:179], v[218:221], v[8:11]
	v_mfma_f32_16x16x32_bf16 v[4:7], v[168:171], v[226:229], v[4:7]
	v_mfma_f32_16x16x32_bf16 v[0:3], v[176:179], v[226:229], v[0:3]
	v_mfma_f32_16x16x32_bf16 v[28:31], v[172:175], v[188:191], v[28:31]
	v_mfma_f32_16x16x32_bf16 v[24:27], v[180:183], v[188:191], v[24:27]
	v_mfma_f32_16x16x32_bf16 v[20:23], v[172:175], v[214:217], v[20:23]
	v_mfma_f32_16x16x32_bf16 v[16:19], v[180:183], v[214:217], v[16:19]
	v_mfma_f32_16x16x32_bf16 v[12:15], v[172:175], v[222:225], v[12:15]
	v_mfma_f32_16x16x32_bf16 v[8:11], v[180:183], v[222:225], v[8:11]
	v_mfma_f32_16x16x32_bf16 v[4:7], v[172:175], v[230:233], v[4:7]
	v_mfma_f32_16x16x32_bf16 v[0:3], v[180:183], v[230:233], v[0:3]
	s_setprio 0
	s_barrier
	s_add_u32 s6, s6, 0x100
	s_addc_u32 s7, s7, 0
	s_add_u32 s34, s34, 0x100
	s_addc_u32 s35, s35, 0
	s_cmp_ge_i32 s60, s44
	s_mov_b32 s30, s60
	s_cbranch_scc0 .LBB0_1812
